# GEMM main loops: removed the redundant s_setprio 0 / s_setprio 1 pair in the middle of each 32-MFMA compute segment
# speedup vs baseline: 1.0012x; 1.0012x over previous
; #define PG8_LDA(dst, b, h) do { _Pragma("unroll") for (int m = 0; m < 4; ++m) _Pragma("unroll") for (int k = 0; k < 2; ++k) dst[m][k] = *(const LAS bf16x8*)(lds + PG8_SA(b, h) + aoff + m * 2048 + k * 1024); } while (0)
; #define PG8_LDB(dst, b, h) do { _Pragma("unroll") for (int n = 0; n < 2; ++n) _Pragma("unroll") for (int k = 0; k < 2; ++k) dst[n][k] = *(const LAS bf16x8*)(lds + PG8_SB(b, h) + boff + n * 2048 + k * 1024); } while (0)
; #define PG8_MMA(ai, bj, At, Bt) do { __builtin_amdgcn_s_setprio(1); _Pragma("unroll") for (int m = 0; m < 4; ++m) _Pragma("unroll") for (int n = 0; n < 2; ++n) _Pragma("unroll") for (int k = 0; k < 2; ++k) \
;         acc[ai][bj][m][n] = __builtin_amdgcn_mfma_f32_16x16x32_bf16(Bt[n][k], At[m][k], acc[ai][bj][m][n], 0, 0, 0); __builtin_amdgcn_s_setprio(0); } while (0)
; #define PG8_WAIT_V(n) asm volatile("s_waitcnt vmcnt(" #n ")" ::: "memory")
; #define PG8_WAIT_L(n) asm volatile("s_waitcnt lgkmcnt(" #n ")" ::: "memory")
; #define PG8_BAR __builtin_amdgcn_s_barrier()
; #define PG8_SCHED __builtin_amdgcn_sched_barrier(0)
; template <class Epi, bool ALIGN_EPI = true, bool SP2 = true>
; DI void gemm_phase(LAS unsigned char* lds, const Gemm g, const StaticOrder& S, const Epi& E) {
;     ...
;             const bool last = (t == nt - 2);
;             const char* a1 = cA + (size_t)(t + 1) * kstep;
;             const char* a2 = last ? nA : cA + (size_t)(t + 2) * kstep; const char* b2 = last ? nB : cB + (size_t)(t + 2) * kstep;
;             const char* a3 = a2 + kstep; const char* b3 = b2 + kstep;
;             if constexpr (SP2) {
;             PG8_LDB(B0, 0, 0); PG8_LDB(B1, 0, 1); PG8_SCHED; PG8_LDA(At, 0, 0); PG8_STAGE(PG8_SA(1, 1), a1 + hstepA, voffA);
;             PG8_WAIT_V(8); PG8_WAIT_L(0); PG8_BAR; PG8_MMA(0, 0, At, B0); PG8_MMA(0, 1, At, B1); PG8_BAR; PG8_SCHED;
;             PG8_LDA(At, 0, 1); PG8_STAGE(PG8_SB(0, 0), b2, voffB); PG8_STAGE(PG8_SB(0, 1), b2 + hstep, voffB); PG8_STAGE(PG8_SA(0, 0), a2, voffA);
.LBB0_536:
	s_add_u32 s18, s16, 0xfffc0080
	s_addc_u32 s19, s17, -1
	s_cmp_eq_u32 s46, 12
	s_cselect_b32 s44, s11, s18
	s_cselect_b32 s45, s1, s19
	s_cselect_b32 s40, s38, vcc_lo
	s_cselect_b32 s41, s9, vcc_hi
	s_add_u32 s18, s44, 0x80
	s_addc_u32 s19, s45, 0
	s_add_i32 s48, 0, 0x10000
	v_add_u32_e32 v136, s48, v143
	s_add_i32 s4, 0, 0x14000
	ds_read_b128 v[128:131], v136
	ds_read_b128 v[150:153], v136 offset:1024
	ds_read_b128 v[154:157], v136 offset:2048
	ds_read_b128 v[158:161], v136 offset:3072
	v_add_u32_e32 v136, s4, v143
	ds_read_b128 v[176:179], v136
	ds_read_b128 v[180:183], v136 offset:1024
	ds_read_b128 v[184:187], v136 offset:2048
	ds_read_b128 v[188:191], v136 offset:3072
	s_mov_b64 s[94:95], s[16:17]
	v_mov_b32_e32 v136, v132
	ds_read_b128 v[192:195], v148
	ds_read_b128 v[196:199], v148 offset:1024
	ds_read_b128 v[200:203], v148 offset:2048
	ds_read_b128 v[204:207], v148 offset:3072
	ds_read_b128 v[208:211], v148 offset:4096
	ds_read_b128 v[212:215], v148 offset:5120
	ds_read_b128 v[216:219], v148 offset:6144
	ds_read_b128 v[220:223], v148 offset:7168
	s_add_i32 m0, s54, 0xc000
	s_nop 0
	global_load_lds_dwordx4 v136, s[94:95]
	v_mov_b32_e32 v136, v134
	s_add_i32 m0, s54, 0xe000
	s_nop 0
	global_load_lds_dwordx4 v136, s[94:95]
	s_waitcnt vmcnt(8)
	s_waitcnt lgkmcnt(0)
	s_barrier
	s_setprio 1
	s_waitcnt lgkmcnt(0)
	v_mfma_f32_16x16x32_bf16 v[124:127], v[128:131], v[192:195], v[124:127]
	v_mfma_f32_16x16x32_bf16 v[120:123], v[154:157], v[192:195], v[120:123]
	v_mfma_f32_16x16x32_bf16 v[116:119], v[128:131], v[200:203], v[116:119]
	v_mfma_f32_16x16x32_bf16 v[108:111], v[154:157], v[200:203], v[108:111]
	v_mfma_f32_16x16x32_bf16 v[100:103], v[128:131], v[208:211], v[100:103]
	v_mfma_f32_16x16x32_bf16 v[92:95], v[154:157], v[208:211], v[92:95]
	v_mfma_f32_16x16x32_bf16 v[84:87], v[128:131], v[216:219], v[84:87]
	v_mfma_f32_16x16x32_bf16 v[76:79], v[154:157], v[216:219], v[76:79]
	v_mfma_f32_16x16x32_bf16 v[124:127], v[150:153], v[196:199], v[124:127]
	v_mfma_f32_16x16x32_bf16 v[120:123], v[158:161], v[196:199], v[120:123]
	v_mfma_f32_16x16x32_bf16 v[116:119], v[150:153], v[204:207], v[116:119]
	v_mfma_f32_16x16x32_bf16 v[108:111], v[158:161], v[204:207], v[108:111]
	v_mfma_f32_16x16x32_bf16 v[100:103], v[150:153], v[212:215], v[100:103]
	v_mfma_f32_16x16x32_bf16 v[92:95], v[158:161], v[212:215], v[92:95]
	v_mfma_f32_16x16x32_bf16 v[84:87], v[150:153], v[220:223], v[84:87]
	v_mfma_f32_16x16x32_bf16 v[76:79], v[158:161], v[220:223], v[76:79]
	v_mfma_f32_16x16x32_bf16 v[112:115], v[176:179], v[192:195], v[112:115]
	v_mfma_f32_16x16x32_bf16 v[104:107], v[184:187], v[192:195], v[104:107]
	v_mfma_f32_16x16x32_bf16 v[96:99], v[176:179], v[200:203], v[96:99]
	v_mfma_f32_16x16x32_bf16 v[88:91], v[184:187], v[200:203], v[88:91]
	v_mfma_f32_16x16x32_bf16 v[80:83], v[176:179], v[208:211], v[80:83]
	v_mfma_f32_16x16x32_bf16 v[72:75], v[184:187], v[208:211], v[72:75]
	v_mfma_f32_16x16x32_bf16 v[68:71], v[176:179], v[216:219], v[68:71]
	v_mfma_f32_16x16x32_bf16 v[64:67], v[184:187], v[216:219], v[64:67]
	v_mfma_f32_16x16x32_bf16 v[112:115], v[180:183], v[196:199], v[112:115]
	v_mfma_f32_16x16x32_bf16 v[104:107], v[188:191], v[196:199], v[104:107]
	v_mfma_f32_16x16x32_bf16 v[96:99], v[180:183], v[204:207], v[96:99]
	v_mfma_f32_16x16x32_bf16 v[88:91], v[188:191], v[204:207], v[88:91]
	v_mfma_f32_16x16x32_bf16 v[80:83], v[180:183], v[212:215], v[80:83]
	v_mfma_f32_16x16x32_bf16 v[72:75], v[188:191], v[212:215], v[72:75]
	v_mfma_f32_16x16x32_bf16 v[68:71], v[180:183], v[220:223], v[68:71]
	v_mfma_f32_16x16x32_bf16 v[64:67], v[188:191], v[220:223], v[64:67]
	s_setprio 0
	s_barrier
	s_mov_b64 s[94:95], s[40:41]
	v_mov_b32_e32 v136, v133
	s_add_i32 s5, s48, s42
	ds_read_b128 v[192:195], v148 offset:16384
	ds_read_b128 v[196:199], v148 offset:17408
	ds_read_b128 v[200:203], v148 offset:18432
	ds_read_b128 v[204:207], v148 offset:19456
	ds_read_b128 v[208:211], v148 offset:20480
	ds_read_b128 v[212:215], v148 offset:21504
	ds_read_b128 v[216:219], v148 offset:22528
	ds_read_b128 v[220:223], v148 offset:23552
	s_mov_b32 m0, s5
	s_nop 0
	global_load_lds_dwordx4 v136, s[94:95]
	v_mov_b32_e32 v136, v135
	s_add_i32 m0, s5, 0x2000
	s_nop 0
	global_load_lds_dwordx4 v136, s[94:95]
	s_add_u32 s94, s40, 0x40000
	s_addc_u32 s95, s41, 0
	v_mov_b32_e32 v136, v133
	s_add_i32 s4, s4, s42
	s_mov_b32 m0, s4
	s_nop 0
	global_load_lds_dwordx4 v136, s[94:95]
	v_mov_b32_e32 v136, v135
	s_add_i32 m0, s4, 0x2000
	s_nop 0
	global_load_lds_dwordx4 v136, s[94:95]
	s_mov_b64 s[94:95], s[44:45]
	v_mov_b32_e32 v136, v132
	s_mov_b32 m0, s54
	s_nop 0
	global_load_lds_dwordx4 v136, s[94:95]
	v_mov_b32_e32 v136, v134
	s_mov_b32 m0, s55
	s_nop 0
	global_load_lds_dwordx4 v136, s[94:95]
	s_waitcnt vmcnt(8)
	s_waitcnt lgkmcnt(0)
	s_barrier
; #define PG8_LDA(dst, b, h) do { _Pragma("unroll") for (int m = 0; m < 4; ++m) _Pragma("unroll") for (int k = 0; k < 2; ++k) dst[m][k] = *(const LAS bf16x8*)(lds + PG8_SA(b, h) + aoff + m * 2048 + k * 1024); } while (0)
; #define PG8_LDB(dst, b, h) do { _Pragma("unroll") for (int n = 0; n < 2; ++n) _Pragma("unroll") for (int k = 0; k < 2; ++k) dst[n][k] = *(const LAS bf16x8*)(lds + PG8_SB(b, h) + boff + n * 2048 + k * 1024); } while (0)
; #define PG8_MMA(ai, bj, At, Bt) do { __builtin_amdgcn_s_setprio(1); _Pragma("unroll") for (int m = 0; m < 4; ++m) _Pragma("unroll") for (int n = 0; n < 2; ++n) _Pragma("unroll") for (int k = 0; k < 2; ++k) \
;         acc[ai][bj][m][n] = __builtin_amdgcn_mfma_f32_16x16x32_bf16(Bt[n][k], At[m][k], acc[ai][bj][m][n], 0, 0, 0); __builtin_amdgcn_s_setprio(0); } while (0)
; #define PG8_WAIT_V(n) asm volatile("s_waitcnt vmcnt(" #n ")" ::: "memory")
; #define PG8_WAIT_L(n) asm volatile("s_waitcnt lgkmcnt(" #n ")" ::: "memory")
; #define PG8_BAR __builtin_amdgcn_s_barrier()
; #define PG8_SCHED __builtin_amdgcn_sched_barrier(0)
; template <class Epi, bool ALIGN_EPI = true, bool SP2 = true>
; DI void gemm_phase(LAS unsigned char* lds, const Gemm g, const StaticOrder& S, const Epi& E) {
;     ...
;             PG8_WAIT_V(8); PG8_WAIT_L(0); PG8_BAR; PG8_MMA(1, 0, At, B0); PG8_MMA(1, 1, At, B1); PG8_BAR; PG8_SCHED;
;             PG8_LDB(B0, 1, 0); PG8_LDB(B1, 1, 1); PG8_SCHED; PG8_LDA(At, 1, 0); PG8_STAGE(PG8_SA(0, 1), a2 + hstepA, voffA);
;             PG8_WAIT_V(8); PG8_WAIT_L(0); PG8_BAR; PG8_MMA(0, 0, At, B0); PG8_MMA(0, 1, At, B1); PG8_BAR; PG8_SCHED;
	s_setprio 1
	s_waitcnt lgkmcnt(0)
	v_mfma_f32_16x16x32_bf16 v[60:63], v[128:131], v[192:195], v[60:63]
	v_mfma_f32_16x16x32_bf16 v[56:59], v[154:157], v[192:195], v[56:59]
	v_mfma_f32_16x16x32_bf16 v[52:55], v[128:131], v[200:203], v[52:55]
	v_mfma_f32_16x16x32_bf16 v[44:47], v[154:157], v[200:203], v[44:47]
	v_mfma_f32_16x16x32_bf16 v[36:39], v[128:131], v[208:211], v[36:39]
	v_mfma_f32_16x16x32_bf16 v[28:31], v[154:157], v[208:211], v[28:31]
	v_mfma_f32_16x16x32_bf16 v[20:23], v[128:131], v[216:219], v[20:23]
	v_mfma_f32_16x16x32_bf16 v[12:15], v[154:157], v[216:219], v[12:15]
	v_mfma_f32_16x16x32_bf16 v[60:63], v[150:153], v[196:199], v[60:63]
	v_mfma_f32_16x16x32_bf16 v[56:59], v[158:161], v[196:199], v[56:59]
	v_mfma_f32_16x16x32_bf16 v[52:55], v[150:153], v[204:207], v[52:55]
	v_mfma_f32_16x16x32_bf16 v[44:47], v[158:161], v[204:207], v[44:47]
	v_mfma_f32_16x16x32_bf16 v[36:39], v[150:153], v[212:215], v[36:39]
	v_mfma_f32_16x16x32_bf16 v[28:31], v[158:161], v[212:215], v[28:31]
	v_mfma_f32_16x16x32_bf16 v[20:23], v[150:153], v[220:223], v[20:23]
	v_mfma_f32_16x16x32_bf16 v[12:15], v[158:161], v[220:223], v[12:15]
	v_mfma_f32_16x16x32_bf16 v[48:51], v[176:179], v[192:195], v[48:51]
	v_mfma_f32_16x16x32_bf16 v[40:43], v[184:187], v[192:195], v[40:43]
	v_mfma_f32_16x16x32_bf16 v[32:35], v[176:179], v[200:203], v[32:35]
	v_mfma_f32_16x16x32_bf16 v[24:27], v[184:187], v[200:203], v[24:27]
	v_mfma_f32_16x16x32_bf16 v[16:19], v[176:179], v[208:211], v[16:19]
	v_mfma_f32_16x16x32_bf16 v[8:11], v[184:187], v[208:211], v[8:11]
	v_mfma_f32_16x16x32_bf16 v[4:7], v[176:179], v[216:219], v[4:7]
	v_mfma_f32_16x16x32_bf16 v[0:3], v[184:187], v[216:219], v[0:3]
	v_mfma_f32_16x16x32_bf16 v[48:51], v[180:183], v[196:199], v[48:51]
	v_mfma_f32_16x16x32_bf16 v[40:43], v[188:191], v[196:199], v[40:43]
	v_mfma_f32_16x16x32_bf16 v[32:35], v[180:183], v[204:207], v[32:35]
	v_mfma_f32_16x16x32_bf16 v[24:27], v[188:191], v[204:207], v[24:27]
	v_mfma_f32_16x16x32_bf16 v[16:19], v[180:183], v[212:215], v[16:19]
	v_mfma_f32_16x16x32_bf16 v[8:11], v[188:191], v[212:215], v[8:11]
	v_mfma_f32_16x16x32_bf16 v[4:7], v[180:183], v[220:223], v[4:7]
	v_mfma_f32_16x16x32_bf16 v[0:3], v[188:191], v[220:223], v[0:3]
	s_setprio 0
	s_barrier
	s_add_i32 s4, 0, 0x18000
	v_add_u32_e32 v136, s4, v143
	s_add_i32 s5, 0, 0x1c000
	ds_read_b128 v[128:131], v136
	ds_read_b128 v[150:153], v136 offset:1024
	ds_read_b128 v[154:157], v136 offset:2048
	ds_read_b128 v[158:161], v136 offset:3072
	v_add_u32_e32 v136, s5, v143
	ds_read_b128 v[176:179], v136
	ds_read_b128 v[180:183], v136 offset:1024
	ds_read_b128 v[184:187], v136 offset:2048
	ds_read_b128 v[188:191], v136 offset:3072
	s_add_u32 s44, s44, 0x40000
	s_addc_u32 s45, s45, 0
	v_mov_b32_e32 v136, v132
	s_mov_b32 m0, s69
	ds_read_b128 v[192:195], v148 offset:32768
	ds_read_b128 v[196:199], v148 offset:33792
	ds_read_b128 v[200:203], v148 offset:34816
	ds_read_b128 v[204:207], v148 offset:35840
	ds_read_b128 v[208:211], v148 offset:36864
	ds_read_b128 v[212:215], v148 offset:37888
	ds_read_b128 v[216:219], v148 offset:38912
	ds_read_b128 v[220:223], v148 offset:39936
	s_nop 0
	global_load_lds_dwordx4 v136, s[44:45]
	v_mov_b32_e32 v136, v134
	s_mov_b32 m0, s70
	s_nop 0
	global_load_lds_dwordx4 v136, s[44:45]
	s_waitcnt vmcnt(8)
	s_waitcnt lgkmcnt(0)
	s_barrier
	s_setprio 1
	s_waitcnt lgkmcnt(0)
	v_mfma_f32_16x16x32_bf16 v[124:127], v[128:131], v[192:195], v[124:127]
	v_mfma_f32_16x16x32_bf16 v[120:123], v[154:157], v[192:195], v[120:123]
	v_mfma_f32_16x16x32_bf16 v[116:119], v[128:131], v[200:203], v[116:119]
	v_mfma_f32_16x16x32_bf16 v[108:111], v[154:157], v[200:203], v[108:111]
	v_mfma_f32_16x16x32_bf16 v[100:103], v[128:131], v[208:211], v[100:103]
	v_mfma_f32_16x16x32_bf16 v[92:95], v[154:157], v[208:211], v[92:95]
	v_mfma_f32_16x16x32_bf16 v[84:87], v[128:131], v[216:219], v[84:87]
	v_mfma_f32_16x16x32_bf16 v[76:79], v[154:157], v[216:219], v[76:79]
	v_mfma_f32_16x16x32_bf16 v[124:127], v[150:153], v[196:199], v[124:127]
	v_mfma_f32_16x16x32_bf16 v[120:123], v[158:161], v[196:199], v[120:123]
	v_mfma_f32_16x16x32_bf16 v[116:119], v[150:153], v[204:207], v[116:119]
	v_mfma_f32_16x16x32_bf16 v[108:111], v[158:161], v[204:207], v[108:111]
	v_mfma_f32_16x16x32_bf16 v[100:103], v[150:153], v[212:215], v[100:103]
	v_mfma_f32_16x16x32_bf16 v[92:95], v[158:161], v[212:215], v[92:95]
	v_mfma_f32_16x16x32_bf16 v[84:87], v[150:153], v[220:223], v[84:87]
	v_mfma_f32_16x16x32_bf16 v[76:79], v[158:161], v[220:223], v[76:79]
	v_mfma_f32_16x16x32_bf16 v[112:115], v[176:179], v[192:195], v[112:115]
	v_mfma_f32_16x16x32_bf16 v[104:107], v[184:187], v[192:195], v[104:107]
	v_mfma_f32_16x16x32_bf16 v[96:99], v[176:179], v[200:203], v[96:99]
	v_mfma_f32_16x16x32_bf16 v[88:91], v[184:187], v[200:203], v[88:91]
	v_mfma_f32_16x16x32_bf16 v[80:83], v[176:179], v[208:211], v[80:83]
	v_mfma_f32_16x16x32_bf16 v[72:75], v[184:187], v[208:211], v[72:75]
	v_mfma_f32_16x16x32_bf16 v[68:71], v[176:179], v[216:219], v[68:71]
	v_mfma_f32_16x16x32_bf16 v[64:67], v[184:187], v[216:219], v[64:67]
	v_mfma_f32_16x16x32_bf16 v[112:115], v[180:183], v[196:199], v[112:115]
	v_mfma_f32_16x16x32_bf16 v[104:107], v[188:191], v[196:199], v[104:107]
	v_mfma_f32_16x16x32_bf16 v[96:99], v[180:183], v[204:207], v[96:99]
	v_mfma_f32_16x16x32_bf16 v[88:91], v[188:191], v[204:207], v[88:91]
	v_mfma_f32_16x16x32_bf16 v[80:83], v[180:183], v[212:215], v[80:83]
	v_mfma_f32_16x16x32_bf16 v[72:75], v[188:191], v[212:215], v[72:75]
	v_mfma_f32_16x16x32_bf16 v[68:71], v[180:183], v[220:223], v[68:71]
	v_mfma_f32_16x16x32_bf16 v[64:67], v[188:191], v[220:223], v[64:67]
	s_setprio 0
	s_barrier
; #define PG8_LDA(dst, b, h) do { _Pragma("unroll") for (int m = 0; m < 4; ++m) _Pragma("unroll") for (int k = 0; k < 2; ++k) dst[m][k] = *(const LAS bf16x8*)(lds + PG8_SA(b, h) + aoff + m * 2048 + k * 1024); } while (0)
; #define PG8_MMA(ai, bj, At, Bt) do { __builtin_amdgcn_s_setprio(1); _Pragma("unroll") for (int m = 0; m < 4; ++m) _Pragma("unroll") for (int n = 0; n < 2; ++n) _Pragma("unroll") for (int k = 0; k < 2; ++k) \
;         acc[ai][bj][m][n] = __builtin_amdgcn_mfma_f32_16x16x32_bf16(Bt[n][k], At[m][k], acc[ai][bj][m][n], 0, 0, 0); __builtin_amdgcn_s_setprio(0); } while (0)
; #define PG8_WAIT_V(n) asm volatile("s_waitcnt vmcnt(" #n ")" ::: "memory")
; #define PG8_WAIT_L(n) asm volatile("s_waitcnt lgkmcnt(" #n ")" ::: "memory")
; #define PG8_BAR __builtin_amdgcn_s_barrier()
; #define PG8_SCHED __builtin_amdgcn_sched_barrier(0)
; template <class Epi, bool ALIGN_EPI = true, bool SP2 = true>
; DI void gemm_phase(LAS unsigned char* lds, const Gemm g, const StaticOrder& S, const Epi& E) {
;     ...
;             PG8_LDA(At, 1, 1); PG8_STAGE(PG8_SB(1, 0), b3, voffB); PG8_STAGE(PG8_SB(1, 1), b3 + hstep, voffB); PG8_STAGE(PG8_SA(1, 0), a3, voffA);
;             PG8_WAIT_V(8); PG8_WAIT_L(0); PG8_BAR; PG8_MMA(1, 0, At, B0); PG8_MMA(1, 1, At, B1); PG8_BAR; PG8_SCHED;
;     ...
;         if constexpr (ALIGN_EPI) { if (wr == 0) PG8_BAR; }
	s_add_u32 s44, s40, 0x80
	s_addc_u32 s45, s41, 0
	v_mov_b32_e32 v136, v133
	s_add_i32 s4, s4, s42
	ds_read_b128 v[192:195], v148 offset:49152
	ds_read_b128 v[196:199], v148 offset:50176
	ds_read_b128 v[200:203], v148 offset:51200
	ds_read_b128 v[204:207], v148 offset:52224
	ds_read_b128 v[208:211], v148 offset:53248
	ds_read_b128 v[212:215], v148 offset:54272
	ds_read_b128 v[216:219], v148 offset:55296
	ds_read_b128 v[220:223], v148 offset:56320
	s_mov_b32 m0, s4
	s_nop 0
	global_load_lds_dwordx4 v136, s[44:45]
	v_mov_b32_e32 v136, v135
	s_add_i32 m0, s4, 0x2000
	s_add_u32 s40, s40, 0x40080
	global_load_lds_dwordx4 v136, s[44:45]
	s_addc_u32 s41, s41, 0
	v_mov_b32_e32 v136, v133
	s_add_i32 s4, s5, s42
	s_mov_b32 m0, s4
	s_nop 0
	global_load_lds_dwordx4 v136, s[40:41]
	v_mov_b32_e32 v136, v135
	s_add_i32 m0, s4, 0x2000
	s_nop 0
	global_load_lds_dwordx4 v136, s[40:41]
	v_mov_b32_e32 v136, v132
	s_mov_b32 m0, s83
	s_nop 0
	global_load_lds_dwordx4 v136, s[18:19]
	v_mov_b32_e32 v136, v134
	s_mov_b32 m0, s86
	s_nop 0
	global_load_lds_dwordx4 v136, s[18:19]
	s_waitcnt vmcnt(8)
	s_waitcnt lgkmcnt(0)
	s_barrier
	s_setprio 1
	s_waitcnt lgkmcnt(0)
	v_mfma_f32_16x16x32_bf16 v[60:63], v[128:131], v[192:195], v[60:63]
	v_mfma_f32_16x16x32_bf16 v[56:59], v[154:157], v[192:195], v[56:59]
	v_mfma_f32_16x16x32_bf16 v[52:55], v[128:131], v[200:203], v[52:55]
	v_mfma_f32_16x16x32_bf16 v[44:47], v[154:157], v[200:203], v[44:47]
	v_mfma_f32_16x16x32_bf16 v[36:39], v[128:131], v[208:211], v[36:39]
	v_mfma_f32_16x16x32_bf16 v[28:31], v[154:157], v[208:211], v[28:31]
	v_mfma_f32_16x16x32_bf16 v[20:23], v[128:131], v[216:219], v[20:23]
	v_mfma_f32_16x16x32_bf16 v[12:15], v[154:157], v[216:219], v[12:15]
	v_mfma_f32_16x16x32_bf16 v[60:63], v[150:153], v[196:199], v[60:63]
	v_mfma_f32_16x16x32_bf16 v[56:59], v[158:161], v[196:199], v[56:59]
	v_mfma_f32_16x16x32_bf16 v[52:55], v[150:153], v[204:207], v[52:55]
	v_mfma_f32_16x16x32_bf16 v[44:47], v[158:161], v[204:207], v[44:47]
	v_mfma_f32_16x16x32_bf16 v[36:39], v[150:153], v[212:215], v[36:39]
	v_mfma_f32_16x16x32_bf16 v[28:31], v[158:161], v[212:215], v[28:31]
	v_mfma_f32_16x16x32_bf16 v[20:23], v[150:153], v[220:223], v[20:23]
	v_mfma_f32_16x16x32_bf16 v[12:15], v[158:161], v[220:223], v[12:15]
	v_mfma_f32_16x16x32_bf16 v[48:51], v[176:179], v[192:195], v[48:51]
	v_mfma_f32_16x16x32_bf16 v[40:43], v[184:187], v[192:195], v[40:43]
	v_mfma_f32_16x16x32_bf16 v[32:35], v[176:179], v[200:203], v[32:35]
	v_mfma_f32_16x16x32_bf16 v[24:27], v[184:187], v[200:203], v[24:27]
	v_mfma_f32_16x16x32_bf16 v[16:19], v[176:179], v[208:211], v[16:19]
	v_mfma_f32_16x16x32_bf16 v[8:11], v[184:187], v[208:211], v[8:11]
	v_mfma_f32_16x16x32_bf16 v[4:7], v[176:179], v[216:219], v[4:7]
	v_mfma_f32_16x16x32_bf16 v[0:3], v[184:187], v[216:219], v[0:3]
	v_mfma_f32_16x16x32_bf16 v[48:51], v[180:183], v[196:199], v[48:51]
	v_mfma_f32_16x16x32_bf16 v[40:43], v[188:191], v[196:199], v[40:43]
	v_mfma_f32_16x16x32_bf16 v[32:35], v[180:183], v[204:207], v[32:35]
	v_mfma_f32_16x16x32_bf16 v[24:27], v[188:191], v[204:207], v[24:27]
	v_mfma_f32_16x16x32_bf16 v[16:19], v[180:183], v[212:215], v[16:19]
	v_mfma_f32_16x16x32_bf16 v[8:11], v[188:191], v[212:215], v[8:11]
	v_mfma_f32_16x16x32_bf16 v[4:7], v[180:183], v[220:223], v[4:7]
	v_mfma_f32_16x16x32_bf16 v[0:3], v[188:191], v[220:223], v[0:3]
	s_setprio 0
	s_barrier
	s_add_i32 s46, s46, 2
	s_add_u32 s16, s16, 0x100
	s_addc_u32 s17, s17, 0
	s_add_u32 vcc_lo, vcc_lo, 0x100
	s_addc_u32 vcc_hi, vcc_hi, 0
	s_cmp_gt_u32 s46, 13
	s_cbranch_scc0 .LBB0_536
	s_and_b64 vcc, exec, s[6:7]
	s_cbranch_vccz .LBB0_539
	s_barrier

; #define PG8_LDA(dst, b, h) do { _Pragma("unroll") for (int m = 0; m < 4; ++m) _Pragma("unroll") for (int k = 0; k < 2; ++k) dst[m][k] = *(const LAS bf16x8*)(lds + PG8_SA(b, h) + aoff + m * 2048 + k * 1024); } while (0)
; #define PG8_LDB(dst, b, h) do { _Pragma("unroll") for (int n = 0; n < 2; ++n) _Pragma("unroll") for (int k = 0; k < 2; ++k) dst[n][k] = *(const LAS bf16x8*)(lds + PG8_SB(b, h) + boff + n * 2048 + k * 1024); } while (0)
; #define PG8_MMA(ai, bj, At, Bt) do { __builtin_amdgcn_s_setprio(1); _Pragma("unroll") for (int m = 0; m < 4; ++m) _Pragma("unroll") for (int n = 0; n < 2; ++n) _Pragma("unroll") for (int k = 0; k < 2; ++k) \
;         acc[ai][bj][m][n] = __builtin_amdgcn_mfma_f32_16x16x32_bf16(Bt[n][k], At[m][k], acc[ai][bj][m][n], 0, 0, 0); __builtin_amdgcn_s_setprio(0); } while (0)
; #define PG8_WAIT_V(n) asm volatile("s_waitcnt vmcnt(" #n ")" ::: "memory")
; #define PG8_WAIT_L(n) asm volatile("s_waitcnt lgkmcnt(" #n ")" ::: "memory")
; #define PG8_BAR __builtin_amdgcn_s_barrier()
; #define PG8_SCHED __builtin_amdgcn_sched_barrier(0)
; template <class Epi, bool ALIGN_EPI = true, bool SP2 = true>
; DI void gemm_phase(LAS unsigned char* lds, const Gemm g, const StaticOrder& S, const Epi& E) {
;     ...
;         const bool has_next = S.next(ui + 1, nxt);
;         const char* nA = has_next ? (const char*)g.A + (size_t)nxt.pm * tstepA : cA; const char* nB = has_next ? (const char*)g.Bt + (size_t)nxt.pn * tstep : cB;
;         for (int t = 0; t < nt; t += 2) {
;             const bool last = (t == nt - 2);
;             const char* a1 = cA + (size_t)(t + 1) * kstep;
;             const char* a2 = last ? nA : cA + (size_t)(t + 2) * kstep; const char* b2 = last ? nB : cB + (size_t)(t + 2) * kstep;
;             const char* a3 = a2 + kstep; const char* b3 = b2 + kstep;
;             if constexpr (SP2) {
;             PG8_LDB(B0, 0, 0); PG8_LDB(B1, 0, 1); PG8_SCHED; PG8_LDA(At, 0, 0); PG8_STAGE(PG8_SA(1, 1), a1 + hstepA, voffA);
;             PG8_WAIT_V(8); PG8_WAIT_L(0); PG8_BAR; PG8_MMA(0, 0, At, B0); PG8_MMA(0, 1, At, B1); PG8_BAR; PG8_SCHED;
;             PG8_LDA(At, 0, 1); PG8_STAGE(PG8_SB(0, 0), b2, voffB); PG8_STAGE(PG8_SB(0, 1), b2 + hstep, voffB); PG8_STAGE(PG8_SA(0, 0), a2, voffA);
.LBB0_556:
	s_ashr_i32 s15, s14, 31
	s_lshl_b64 s[6:7], s[14:15], 17
	v_readlane_b32 s8, v254, 25
	s_add_u32 s40, s8, s6
	v_readlane_b32 s6, v254, 26
	s_addc_u32 s41, s6, s7
	s_and_b64 s[6:7], s[2:3], exec
	s_cselect_b32 s49, s41, s17
	s_cselect_b32 s48, s40, s16
	s_ashr_i32 s13, s12, 31
	s_lshl_b64 s[6:7], s[12:13], 17
	s_add_u32 s18, s26, s6
	s_addc_u32 s19, s34, s7
	s_and_b64 s[6:7], s[2:3], exec
	s_cselect_b32 s45, s19, s47
	s_cselect_b32 s44, s18, s46
	s_add_u32 s8, s16, 0x100
	s_addc_u32 s9, s17, 0
	s_add_u32 s42, s46, 0x100
	s_addc_u32 s43, s47, 0
	s_add_u32 s6, s16, 0x180
	s_addc_u32 s7, s17, 0
	s_add_i32 s86, 0, 0x10000
	s_add_i32 s96, 0, 0x14000
	v_add_u32_e32 v134, s86, v132
	v_add_u32_e32 v135, s96, v132
	ds_read_b128 v[0:3], v134
	ds_read_b128 v[4:7], v134 offset:1024
	ds_read_b128 v[8:11], v134 offset:2048
	ds_read_b128 v[12:15], v134 offset:3072
	ds_read_b128 v[16:19], v135
	ds_read_b128 v[20:23], v135 offset:1024
	ds_read_b128 v[24:27], v135 offset:2048
	ds_read_b128 v[28:31], v135 offset:3072
	v_mov_b32_e32 v169, 0x41b17218
	v_mov_b64_e32 v[160:161], 0x400
	v_mov_b32_e32 v143, 0x3eaaaaab
	s_add_u32 s94, s16, 0x10080
	s_addc_u32 s95, s17, 0
	v_mov_b32_e32 v64, v128
	s_add_i32 s92, s54, 0xc000
	ds_read_b128 v[32:35], v133
	ds_read_b128 v[36:39], v133 offset:1024
	ds_read_b128 v[40:43], v133 offset:2048
	ds_read_b128 v[44:47], v133 offset:3072
	ds_read_b128 v[48:51], v133 offset:4096
	ds_read_b128 v[52:55], v133 offset:5120
	ds_read_b128 v[56:59], v133 offset:6144
	ds_read_b128 v[60:63], v133 offset:7168
	s_mov_b32 m0, s92
	s_add_i32 s13, s54, 0xe000
	global_load_lds_dwordx4 v64, s[94:95]
	v_mov_b32_e32 v64, v130
	s_mov_b32 m0, s13
	s_nop 0
	global_load_lds_dwordx4 v64, s[94:95]
	s_waitcnt vmcnt(8)
	s_waitcnt lgkmcnt(0)
	s_barrier
	s_setprio 1
	s_waitcnt lgkmcnt(0)
	v_mfma_f32_16x16x32_bf16 v[64:67], v[0:3], v[32:35], 0
	v_mfma_f32_16x16x32_bf16 v[68:71], v[8:11], v[32:35], 0
	v_mfma_f32_16x16x32_bf16 v[72:75], v[0:3], v[40:43], 0
	v_mfma_f32_16x16x32_bf16 v[76:79], v[8:11], v[40:43], 0
	v_mfma_f32_16x16x32_bf16 v[80:83], v[0:3], v[48:51], 0
	v_mfma_f32_16x16x32_bf16 v[84:87], v[8:11], v[48:51], 0
	v_mfma_f32_16x16x32_bf16 v[88:91], v[0:3], v[56:59], 0
	v_mfma_f32_16x16x32_bf16 v[92:95], v[8:11], v[56:59], 0
	v_mfma_f32_16x16x32_bf16 v[64:67], v[4:7], v[36:39], v[64:67]
	v_mfma_f32_16x16x32_bf16 v[68:71], v[12:15], v[36:39], v[68:71]
	v_mfma_f32_16x16x32_bf16 v[72:75], v[4:7], v[44:47], v[72:75]
	v_mfma_f32_16x16x32_bf16 v[76:79], v[12:15], v[44:47], v[76:79]
	v_mfma_f32_16x16x32_bf16 v[80:83], v[4:7], v[52:55], v[80:83]
	v_mfma_f32_16x16x32_bf16 v[84:87], v[12:15], v[52:55], v[84:87]
	v_mfma_f32_16x16x32_bf16 v[88:91], v[4:7], v[60:63], v[88:91]
	v_mfma_f32_16x16x32_bf16 v[92:95], v[12:15], v[60:63], v[92:95]
	v_mfma_f32_16x16x32_bf16 v[96:99], v[16:19], v[32:35], 0
	v_mfma_f32_16x16x32_bf16 v[32:35], v[24:27], v[32:35], 0
	v_mfma_f32_16x16x32_bf16 v[96:99], v[20:23], v[36:39], v[96:99]
	v_mfma_f32_16x16x32_bf16 v[32:35], v[28:31], v[36:39], v[32:35]
	v_mfma_f32_16x16x32_bf16 v[36:39], v[16:19], v[40:43], 0
	v_mfma_f32_16x16x32_bf16 v[40:43], v[24:27], v[40:43], 0
	v_mfma_f32_16x16x32_bf16 v[36:39], v[20:23], v[44:47], v[36:39]
	v_mfma_f32_16x16x32_bf16 v[40:43], v[28:31], v[44:47], v[40:43]
	v_mfma_f32_16x16x32_bf16 v[44:47], v[16:19], v[48:51], 0
	v_mfma_f32_16x16x32_bf16 v[48:51], v[24:27], v[48:51], 0
	v_mfma_f32_16x16x32_bf16 v[44:47], v[20:23], v[52:55], v[44:47]
	v_mfma_f32_16x16x32_bf16 v[48:51], v[28:31], v[52:55], v[48:51]
	v_mfma_f32_16x16x32_bf16 v[52:55], v[16:19], v[56:59], 0
	v_mfma_f32_16x16x32_bf16 v[56:59], v[24:27], v[56:59], 0
	v_mfma_f32_16x16x32_bf16 v[52:55], v[20:23], v[60:63], v[52:55]
	v_mfma_f32_16x16x32_bf16 v[56:59], v[28:31], v[60:63], v[56:59]
	s_setprio 0
	s_barrier
	v_mov_b32_e32 v136, v129
	s_add_i32 s86, s86, s36
	ds_read_b128 v[60:63], v133 offset:16384
	ds_read_b128 v[100:103], v133 offset:17408
	ds_read_b128 v[104:107], v133 offset:18432
	ds_read_b128 v[108:111], v133 offset:19456
	ds_read_b128 v[112:115], v133 offset:20480
	ds_read_b128 v[116:119], v133 offset:21504
	ds_read_b128 v[120:123], v133 offset:22528
	ds_read_b128 v[124:127], v133 offset:23552
	s_mov_b32 m0, s86
	s_add_i32 s15, s86, 0x2000
	global_load_lds_dwordx4 v136, s[42:43]
	v_mov_b32_e32 v136, v131
	s_mov_b32 m0, s15
	s_add_u32 s94, s46, 0x10100
	global_load_lds_dwordx4 v136, s[42:43]
	s_addc_u32 s95, s47, 0
	v_mov_b32_e32 v136, v129
	s_add_i32 s42, s96, s36
	s_mov_b32 m0, s42
	s_add_i32 s43, s42, 0x2000
	global_load_lds_dwordx4 v136, s[94:95]
	v_mov_b32_e32 v136, v131
	s_mov_b32 m0, s43
	s_nop 0
	global_load_lds_dwordx4 v136, s[94:95]
	v_mov_b32_e32 v136, v128
	s_mov_b32 m0, s54
	s_nop 0
	global_load_lds_dwordx4 v136, s[8:9]
	v_mov_b32_e32 v136, v130
	s_mov_b32 m0, s55
	s_nop 0
	global_load_lds_dwordx4 v136, s[8:9]
	s_waitcnt vmcnt(8)
	s_waitcnt lgkmcnt(0)
	s_barrier
; #define PG8_LDA(dst, b, h) do { _Pragma("unroll") for (int m = 0; m < 4; ++m) _Pragma("unroll") for (int k = 0; k < 2; ++k) dst[m][k] = *(const LAS bf16x8*)(lds + PG8_SA(b, h) + aoff + m * 2048 + k * 1024); } while (0)
; #define PG8_LDB(dst, b, h) do { _Pragma("unroll") for (int n = 0; n < 2; ++n) _Pragma("unroll") for (int k = 0; k < 2; ++k) dst[n][k] = *(const LAS bf16x8*)(lds + PG8_SB(b, h) + boff + n * 2048 + k * 1024); } while (0)
; #define PG8_MMA(ai, bj, At, Bt) do { __builtin_amdgcn_s_setprio(1); _Pragma("unroll") for (int m = 0; m < 4; ++m) _Pragma("unroll") for (int n = 0; n < 2; ++n) _Pragma("unroll") for (int k = 0; k < 2; ++k) \
;         acc[ai][bj][m][n] = __builtin_amdgcn_mfma_f32_16x16x32_bf16(Bt[n][k], At[m][k], acc[ai][bj][m][n], 0, 0, 0); __builtin_amdgcn_s_setprio(0); } while (0)
; #define PG8_WAIT_V(n) asm volatile("s_waitcnt vmcnt(" #n ")" ::: "memory")
; #define PG8_WAIT_L(n) asm volatile("s_waitcnt lgkmcnt(" #n ")" ::: "memory")
; #define PG8_BAR __builtin_amdgcn_s_barrier()
; #define PG8_SCHED __builtin_amdgcn_sched_barrier(0)
; template <class Epi, bool ALIGN_EPI = true, bool SP2 = true>
; DI void gemm_phase(LAS unsigned char* lds, const Gemm g, const StaticOrder& S, const Epi& E) {
;     ...
;             PG8_WAIT_V(8); PG8_WAIT_L(0); PG8_BAR; PG8_MMA(1, 0, At, B0); PG8_MMA(1, 1, At, B1); PG8_BAR; PG8_SCHED;
;             PG8_LDB(B0, 1, 0); PG8_LDB(B1, 1, 1); PG8_SCHED; PG8_LDA(At, 1, 0); PG8_STAGE(PG8_SA(0, 1), a2 + hstepA, voffA);
;             PG8_WAIT_V(8); PG8_WAIT_L(0); PG8_BAR; PG8_MMA(0, 0, At, B0); PG8_MMA(0, 1, At, B1); PG8_BAR; PG8_SCHED;
	s_setprio 1
	s_waitcnt lgkmcnt(0)
	v_mfma_f32_16x16x32_bf16 v[148:151], v[0:3], v[60:63], 0
	v_mfma_f32_16x16x32_bf16 v[156:159], v[0:3], v[104:107], 0
	v_mfma_f32_16x16x32_bf16 v[180:183], v[0:3], v[112:115], 0
	v_mfma_f32_16x16x32_bf16 v[0:3], v[0:3], v[120:123], 0
	v_mfma_f32_16x16x32_bf16 v[148:151], v[4:7], v[100:103], v[148:151]
	v_mfma_f32_16x16x32_bf16 v[156:159], v[4:7], v[108:111], v[156:159]
	v_mfma_f32_16x16x32_bf16 v[180:183], v[4:7], v[116:119], v[180:183]
	v_mfma_f32_16x16x32_bf16 v[0:3], v[4:7], v[124:127], v[0:3]
	v_mfma_f32_16x16x32_bf16 v[4:7], v[8:11], v[120:123], 0
	v_mfma_f32_16x16x32_bf16 v[152:155], v[8:11], v[60:63], 0
	v_mfma_f32_16x16x32_bf16 v[176:179], v[8:11], v[104:107], 0
	v_mfma_f32_16x16x32_bf16 v[184:187], v[8:11], v[112:115], 0
	v_mfma_f32_16x16x32_bf16 v[4:7], v[12:15], v[124:127], v[4:7]
	v_mfma_f32_16x16x32_bf16 v[152:155], v[12:15], v[100:103], v[152:155]
	v_mfma_f32_16x16x32_bf16 v[176:179], v[12:15], v[108:111], v[176:179]
	v_mfma_f32_16x16x32_bf16 v[184:187], v[12:15], v[116:119], v[184:187]
	v_mfma_f32_16x16x32_bf16 v[8:11], v[16:19], v[60:63], 0
	v_mfma_f32_16x16x32_bf16 v[12:15], v[24:27], v[60:63], 0
	v_mfma_f32_16x16x32_bf16 v[8:11], v[20:23], v[100:103], v[8:11]
	v_mfma_f32_16x16x32_bf16 v[12:15], v[28:31], v[100:103], v[12:15]
	v_mfma_f32_16x16x32_bf16 v[60:63], v[16:19], v[104:107], 0
	v_mfma_f32_16x16x32_bf16 v[100:103], v[24:27], v[104:107], 0
	v_mfma_f32_16x16x32_bf16 v[104:107], v[16:19], v[112:115], 0
	v_mfma_f32_16x16x32_bf16 v[16:19], v[16:19], v[120:123], 0
	v_mfma_f32_16x16x32_bf16 v[60:63], v[20:23], v[108:111], v[60:63]
	v_mfma_f32_16x16x32_bf16 v[100:103], v[28:31], v[108:111], v[100:103]
	v_mfma_f32_16x16x32_bf16 v[104:107], v[20:23], v[116:119], v[104:107]
	v_mfma_f32_16x16x32_bf16 v[108:111], v[24:27], v[112:115], 0
	v_mfma_f32_16x16x32_bf16 v[16:19], v[20:23], v[124:127], v[16:19]
	v_mfma_f32_16x16x32_bf16 v[20:23], v[24:27], v[120:123], 0
	v_mfma_f32_16x16x32_bf16 v[108:111], v[28:31], v[116:119], v[108:111]
	v_mfma_f32_16x16x32_bf16 v[20:23], v[28:31], v[124:127], v[20:23]
	s_setprio 0
	s_barrier
	s_add_i32 s96, 0, 0x18000
	s_add_i32 s97, 0, 0x1c000
	v_add_u32_e32 v136, s96, v132
	v_add_u32_e32 v138, s97, v132
	ds_read_b128 v[24:27], v136
	ds_read_b128 v[28:31], v136 offset:1024
	ds_read_b128 v[112:115], v136 offset:2048
	ds_read_b128 v[116:119], v136 offset:3072
	ds_read_b128 v[120:123], v138
	ds_read_b128 v[124:127], v138 offset:1024
	ds_read_b128 v[188:191], v138 offset:2048
	ds_read_b128 v[192:195], v138 offset:3072
	s_add_u32 s8, s16, 0x10100
	s_addc_u32 s9, s17, 0
	v_mov_b32_e32 v139, v128
	s_mov_b32 m0, s69
	ds_read_b128 v[196:199], v133 offset:32768
	ds_read_b128 v[200:203], v133 offset:33792
	ds_read_b128 v[204:207], v133 offset:34816
	ds_read_b128 v[208:211], v133 offset:35840
	ds_read_b128 v[212:215], v133 offset:36864
	ds_read_b128 v[216:219], v133 offset:37888
	ds_read_b128 v[220:223], v133 offset:38912
	ds_read_b128 v[224:227], v133 offset:39936
	s_nop 0
	global_load_lds_dwordx4 v139, s[8:9]
	v_mov_b32_e32 v139, v130
	s_mov_b32 m0, s70
	s_nop 0
	global_load_lds_dwordx4 v139, s[8:9]
	s_waitcnt vmcnt(8)
	s_waitcnt lgkmcnt(0)
	s_barrier
	s_setprio 1
	s_waitcnt lgkmcnt(0)
	v_mfma_f32_16x16x32_bf16 v[64:67], v[24:27], v[196:199], v[64:67]
	v_mfma_f32_16x16x32_bf16 v[68:71], v[112:115], v[196:199], v[68:71]
	v_mfma_f32_16x16x32_bf16 v[72:75], v[24:27], v[204:207], v[72:75]
	v_mfma_f32_16x16x32_bf16 v[76:79], v[112:115], v[204:207], v[76:79]
	v_mfma_f32_16x16x32_bf16 v[80:83], v[24:27], v[212:215], v[80:83]
	v_mfma_f32_16x16x32_bf16 v[84:87], v[112:115], v[212:215], v[84:87]
	v_mfma_f32_16x16x32_bf16 v[88:91], v[24:27], v[220:223], v[88:91]
	v_mfma_f32_16x16x32_bf16 v[92:95], v[112:115], v[220:223], v[92:95]
	v_mfma_f32_16x16x32_bf16 v[64:67], v[28:31], v[200:203], v[64:67]
	v_mfma_f32_16x16x32_bf16 v[68:71], v[116:119], v[200:203], v[68:71]
	v_mfma_f32_16x16x32_bf16 v[72:75], v[28:31], v[208:211], v[72:75]
	v_mfma_f32_16x16x32_bf16 v[76:79], v[116:119], v[208:211], v[76:79]
	v_mfma_f32_16x16x32_bf16 v[80:83], v[28:31], v[216:219], v[80:83]
	v_mfma_f32_16x16x32_bf16 v[84:87], v[116:119], v[216:219], v[84:87]
	v_mfma_f32_16x16x32_bf16 v[88:91], v[28:31], v[224:227], v[88:91]
	v_mfma_f32_16x16x32_bf16 v[92:95], v[116:119], v[224:227], v[92:95]
	v_mfma_f32_16x16x32_bf16 v[96:99], v[120:123], v[196:199], v[96:99]
	v_mfma_f32_16x16x32_bf16 v[32:35], v[188:191], v[196:199], v[32:35]
	v_mfma_f32_16x16x32_bf16 v[36:39], v[120:123], v[204:207], v[36:39]
	v_mfma_f32_16x16x32_bf16 v[40:43], v[188:191], v[204:207], v[40:43]
	v_mfma_f32_16x16x32_bf16 v[44:47], v[120:123], v[212:215], v[44:47]
	v_mfma_f32_16x16x32_bf16 v[48:51], v[188:191], v[212:215], v[48:51]
	v_mfma_f32_16x16x32_bf16 v[52:55], v[120:123], v[220:223], v[52:55]
	v_mfma_f32_16x16x32_bf16 v[56:59], v[188:191], v[220:223], v[56:59]
	v_mfma_f32_16x16x32_bf16 v[96:99], v[124:127], v[200:203], v[96:99]
	v_mfma_f32_16x16x32_bf16 v[32:35], v[192:195], v[200:203], v[32:35]
	v_mfma_f32_16x16x32_bf16 v[36:39], v[124:127], v[208:211], v[36:39]
	v_mfma_f32_16x16x32_bf16 v[40:43], v[192:195], v[208:211], v[40:43]
	v_mfma_f32_16x16x32_bf16 v[44:47], v[124:127], v[216:219], v[44:47]
	v_mfma_f32_16x16x32_bf16 v[48:51], v[192:195], v[216:219], v[48:51]
	v_mfma_f32_16x16x32_bf16 v[52:55], v[124:127], v[224:227], v[52:55]
	v_mfma_f32_16x16x32_bf16 v[56:59], v[192:195], v[224:227], v[56:59]
	s_setprio 0
	s_barrier
; #define PG8_LDA(dst, b, h) do { _Pragma("unroll") for (int m = 0; m < 4; ++m) _Pragma("unroll") for (int k = 0; k < 2; ++k) dst[m][k] = *(const LAS bf16x8*)(lds + PG8_SA(b, h) + aoff + m * 2048 + k * 1024); } while (0)
; #define PG8_LDB(dst, b, h) do { _Pragma("unroll") for (int n = 0; n < 2; ++n) _Pragma("unroll") for (int k = 0; k < 2; ++k) dst[n][k] = *(const LAS bf16x8*)(lds + PG8_SB(b, h) + boff + n * 2048 + k * 1024); } while (0)
; #define PG8_MMA(ai, bj, At, Bt) do { __builtin_amdgcn_s_setprio(1); _Pragma("unroll") for (int m = 0; m < 4; ++m) _Pragma("unroll") for (int n = 0; n < 2; ++n) _Pragma("unroll") for (int k = 0; k < 2; ++k) \
;         acc[ai][bj][m][n] = __builtin_amdgcn_mfma_f32_16x16x32_bf16(Bt[n][k], At[m][k], acc[ai][bj][m][n], 0, 0, 0); __builtin_amdgcn_s_setprio(0); } while (0)
; #define PG8_WAIT_V(n) asm volatile("s_waitcnt vmcnt(" #n ")" ::: "memory")
; #define PG8_WAIT_L(n) asm volatile("s_waitcnt lgkmcnt(" #n ")" ::: "memory")
; #define PG8_BAR __builtin_amdgcn_s_barrier()
; #define PG8_SCHED __builtin_amdgcn_sched_barrier(0)
; template <class Epi, bool ALIGN_EPI = true, bool SP2 = true>
; DI void gemm_phase(LAS unsigned char* lds, const Gemm g, const StaticOrder& S, const Epi& E) {
;     ...
;             PG8_LDB(B0, 0, 0); PG8_LDB(B1, 0, 1); PG8_SCHED; PG8_LDA(At, 0, 0); PG8_STAGE(PG8_SA(1, 1), a1 + hstepA, voffA);
;             PG8_WAIT_V(8); PG8_WAIT_L(0); PG8_BAR; PG8_MMA(0, 0, At, B0); PG8_MMA(0, 1, At, B1); PG8_BAR; PG8_SCHED;
;     ...
;             PG8_LDA(At, 1, 1); PG8_STAGE(PG8_SB(1, 0), b3, voffB); PG8_STAGE(PG8_SB(1, 1), b3 + hstep, voffB); PG8_STAGE(PG8_SA(1, 0), a3, voffA);
;             PG8_WAIT_V(8); PG8_WAIT_L(0); PG8_BAR; PG8_MMA(1, 0, At, B0); PG8_MMA(1, 1, At, B1); PG8_BAR; PG8_SCHED;
	s_add_u32 s94, s46, 0x180
	s_addc_u32 s95, s47, 0
	v_mov_b32_e32 v139, v129
	s_add_i32 s96, s96, s36
	ds_read_b128 v[196:199], v133 offset:49152
	ds_read_b128 v[200:203], v133 offset:50176
	ds_read_b128 v[204:207], v133 offset:51200
	ds_read_b128 v[208:211], v133 offset:52224
	ds_read_b128 v[212:215], v133 offset:53248
	ds_read_b128 v[216:219], v133 offset:54272
	ds_read_b128 v[220:223], v133 offset:55296
	ds_read_b128 v[224:227], v133 offset:56320
	s_mov_b32 m0, s96
	s_add_i32 s8, s96, 0x2000
	global_load_lds_dwordx4 v139, s[94:95]
	v_mov_b32_e32 v139, v131
	s_mov_b32 m0, s8
	s_nop 0
	global_load_lds_dwordx4 v139, s[94:95]
	s_add_u32 s94, s46, 0x10180
	s_addc_u32 s95, s47, 0
	v_mov_b32_e32 v139, v129
	s_add_i32 s9, s97, s36
	s_mov_b32 m0, s9
	s_add_i32 s46, s9, 0x2000
	global_load_lds_dwordx4 v139, s[94:95]
	v_mov_b32_e32 v139, v131
	s_mov_b32 m0, s46
	s_nop 0
	global_load_lds_dwordx4 v139, s[94:95]
	v_mov_b32_e32 v139, v128
	s_mov_b32 m0, s73
	s_nop 0
	global_load_lds_dwordx4 v139, s[6:7]
	v_mov_b32_e32 v139, v130
	s_mov_b32 m0, s81
	s_nop 0
	global_load_lds_dwordx4 v139, s[6:7]
	s_waitcnt vmcnt(8)
	s_waitcnt lgkmcnt(0)
	s_barrier
	s_setprio 1
	s_waitcnt lgkmcnt(0)
	v_mfma_f32_16x16x32_bf16 v[0:3], v[24:27], v[220:223], v[0:3]
	v_mfma_f32_16x16x32_bf16 v[4:7], v[112:115], v[220:223], v[4:7]
	v_mfma_f32_16x16x32_bf16 v[148:151], v[24:27], v[196:199], v[148:151]
	v_mfma_f32_16x16x32_bf16 v[152:155], v[112:115], v[196:199], v[152:155]
	v_mfma_f32_16x16x32_bf16 v[156:159], v[24:27], v[204:207], v[156:159]
	v_mfma_f32_16x16x32_bf16 v[176:179], v[112:115], v[204:207], v[176:179]
	v_mfma_f32_16x16x32_bf16 v[180:183], v[24:27], v[212:215], v[180:183]
	v_mfma_f32_16x16x32_bf16 v[184:187], v[112:115], v[212:215], v[184:187]
	v_mfma_f32_16x16x32_bf16 v[0:3], v[28:31], v[224:227], v[0:3]
	v_mfma_f32_16x16x32_bf16 v[4:7], v[116:119], v[224:227], v[4:7]
	v_mfma_f32_16x16x32_bf16 v[148:151], v[28:31], v[200:203], v[148:151]
	v_mfma_f32_16x16x32_bf16 v[152:155], v[116:119], v[200:203], v[152:155]
	v_mfma_f32_16x16x32_bf16 v[156:159], v[28:31], v[208:211], v[156:159]
	v_mfma_f32_16x16x32_bf16 v[176:179], v[116:119], v[208:211], v[176:179]
	v_mfma_f32_16x16x32_bf16 v[180:183], v[28:31], v[216:219], v[180:183]
	v_mfma_f32_16x16x32_bf16 v[184:187], v[116:119], v[216:219], v[184:187]
	v_mfma_f32_16x16x32_bf16 v[8:11], v[120:123], v[196:199], v[8:11]
	v_mfma_f32_16x16x32_bf16 v[12:15], v[188:191], v[196:199], v[12:15]
	v_mfma_f32_16x16x32_bf16 v[24:27], v[120:123], v[204:207], v[60:63]
	v_mfma_f32_16x16x32_bf16 v[28:31], v[188:191], v[204:207], v[100:103]
	v_mfma_f32_16x16x32_bf16 v[60:63], v[120:123], v[212:215], v[104:107]
	v_mfma_f32_16x16x32_bf16 v[100:103], v[188:191], v[212:215], v[108:111]
	v_mfma_f32_16x16x32_bf16 v[16:19], v[120:123], v[220:223], v[16:19]
	v_mfma_f32_16x16x32_bf16 v[20:23], v[188:191], v[220:223], v[20:23]
	v_mfma_f32_16x16x32_bf16 v[8:11], v[124:127], v[200:203], v[8:11]
	v_mfma_f32_16x16x32_bf16 v[12:15], v[192:195], v[200:203], v[12:15]
	v_mfma_f32_16x16x32_bf16 v[24:27], v[124:127], v[208:211], v[24:27]
	v_mfma_f32_16x16x32_bf16 v[28:31], v[192:195], v[208:211], v[28:31]
	v_mfma_f32_16x16x32_bf16 v[60:63], v[124:127], v[216:219], v[60:63]
	v_mfma_f32_16x16x32_bf16 v[100:103], v[192:195], v[216:219], v[100:103]
	v_mfma_f32_16x16x32_bf16 v[16:19], v[124:127], v[224:227], v[16:19]
	v_mfma_f32_16x16x32_bf16 v[20:23], v[192:195], v[224:227], v[20:23]
	s_setprio 0
	s_barrier
	ds_read_b128 v[104:107], v134
	ds_read_b128 v[108:111], v134 offset:1024
	ds_read_b128 v[112:115], v134 offset:2048
	ds_read_b128 v[116:119], v134 offset:3072
	ds_read_b128 v[120:123], v135
	ds_read_b128 v[124:127], v135 offset:1024
	ds_read_b128 v[188:191], v135 offset:2048
	ds_read_b128 v[192:195], v135 offset:3072
	s_add_u32 s6, s48, 0x80
	s_addc_u32 s7, s49, 0
	s_add_u32 s16, s16, 0x10180
	s_addc_u32 s17, s17, 0
	v_mov_b32_e32 v134, v128
	s_mov_b32 m0, s92
	ds_read_b128 v[196:199], v133
	ds_read_b128 v[200:203], v133 offset:1024
	ds_read_b128 v[204:207], v133 offset:2048
	ds_read_b128 v[208:211], v133 offset:3072
	ds_read_b128 v[212:215], v133 offset:4096
	ds_read_b128 v[216:219], v133 offset:5120
	ds_read_b128 v[220:223], v133 offset:6144
	ds_read_b128 v[224:227], v133 offset:7168
	s_nop 0
	global_load_lds_dwordx4 v134, s[16:17]
	v_mov_b32_e32 v134, v130
	s_mov_b32 m0, s13
	s_nop 0
	global_load_lds_dwordx4 v134, s[16:17]
	s_waitcnt vmcnt(8)
	s_waitcnt lgkmcnt(0)
	s_barrier
	s_setprio 1
	s_waitcnt lgkmcnt(0)
	v_mfma_f32_16x16x32_bf16 v[64:67], v[104:107], v[196:199], v[64:67]
	v_mfma_f32_16x16x32_bf16 v[68:71], v[112:115], v[196:199], v[68:71]
	v_mfma_f32_16x16x32_bf16 v[72:75], v[104:107], v[204:207], v[72:75]
	v_mfma_f32_16x16x32_bf16 v[76:79], v[112:115], v[204:207], v[76:79]
	v_mfma_f32_16x16x32_bf16 v[80:83], v[104:107], v[212:215], v[80:83]
	v_mfma_f32_16x16x32_bf16 v[84:87], v[112:115], v[212:215], v[84:87]
	v_mfma_f32_16x16x32_bf16 v[88:91], v[104:107], v[220:223], v[88:91]
	v_mfma_f32_16x16x32_bf16 v[92:95], v[112:115], v[220:223], v[92:95]
	v_mfma_f32_16x16x32_bf16 v[64:67], v[108:111], v[200:203], v[64:67]
	v_mfma_f32_16x16x32_bf16 v[68:71], v[116:119], v[200:203], v[68:71]
	v_mfma_f32_16x16x32_bf16 v[72:75], v[108:111], v[208:211], v[72:75]
	v_mfma_f32_16x16x32_bf16 v[76:79], v[116:119], v[208:211], v[76:79]
	v_mfma_f32_16x16x32_bf16 v[80:83], v[108:111], v[216:219], v[80:83]
	v_mfma_f32_16x16x32_bf16 v[84:87], v[116:119], v[216:219], v[84:87]
	v_mfma_f32_16x16x32_bf16 v[88:91], v[108:111], v[224:227], v[88:91]
	v_mfma_f32_16x16x32_bf16 v[92:95], v[116:119], v[224:227], v[92:95]
	v_mfma_f32_16x16x32_bf16 v[36:39], v[120:123], v[204:207], v[36:39]
	v_mfma_f32_16x16x32_bf16 v[96:99], v[120:123], v[196:199], v[96:99]
	v_mfma_f32_16x16x32_bf16 v[32:35], v[188:191], v[196:199], v[32:35]
	v_mfma_f32_16x16x32_bf16 v[196:199], v[124:127], v[208:211], v[36:39]
	v_mfma_f32_16x16x32_bf16 v[36:39], v[188:191], v[204:207], v[40:43]
	v_mfma_f32_16x16x32_bf16 v[40:43], v[192:195], v[208:211], v[36:39]
	v_mfma_f32_16x16x32_bf16 v[36:39], v[120:123], v[212:215], v[44:47]
	v_mfma_f32_16x16x32_bf16 v[96:99], v[124:127], v[200:203], v[96:99]
	v_mfma_f32_16x16x32_bf16 v[32:35], v[192:195], v[200:203], v[32:35]
	v_mfma_f32_16x16x32_bf16 v[200:203], v[124:127], v[216:219], v[36:39]
	v_mfma_f32_16x16x32_bf16 v[36:39], v[188:191], v[212:215], v[48:51]
	v_mfma_f32_16x16x32_bf16 v[48:51], v[192:195], v[216:219], v[36:39]
	v_mfma_f32_16x16x32_bf16 v[36:39], v[120:123], v[220:223], v[52:55]
	v_mfma_f32_16x16x32_bf16 v[52:55], v[124:127], v[224:227], v[36:39]
	v_mfma_f32_16x16x32_bf16 v[36:39], v[188:191], v[220:223], v[56:59]
	v_mfma_f32_16x16x32_bf16 v[56:59], v[192:195], v[224:227], v[36:39]
	s_setprio 0
	s_barrier
; #define PG8_LDA(dst, b, h) do { _Pragma("unroll") for (int m = 0; m < 4; ++m) _Pragma("unroll") for (int k = 0; k < 2; ++k) dst[m][k] = *(const LAS bf16x8*)(lds + PG8_SA(b, h) + aoff + m * 2048 + k * 1024); } while (0)
; #define PG8_LDB(dst, b, h) do { _Pragma("unroll") for (int n = 0; n < 2; ++n) _Pragma("unroll") for (int k = 0; k < 2; ++k) dst[n][k] = *(const LAS bf16x8*)(lds + PG8_SB(b, h) + boff + n * 2048 + k * 1024); } while (0)
; #define PG8_MMA(ai, bj, At, Bt) do { __builtin_amdgcn_s_setprio(1); _Pragma("unroll") for (int m = 0; m < 4; ++m) _Pragma("unroll") for (int n = 0; n < 2; ++n) _Pragma("unroll") for (int k = 0; k < 2; ++k) \
;         acc[ai][bj][m][n] = __builtin_amdgcn_mfma_f32_16x16x32_bf16(Bt[n][k], At[m][k], acc[ai][bj][m][n], 0, 0, 0); __builtin_amdgcn_s_setprio(0); } while (0)
; #define PG8_WAIT_V(n) asm volatile("s_waitcnt vmcnt(" #n ")" ::: "memory")
; #define PG8_WAIT_L(n) asm volatile("s_waitcnt lgkmcnt(" #n ")" ::: "memory")
; #define PG8_BAR __builtin_amdgcn_s_barrier()
; #define PG8_SCHED __builtin_amdgcn_sched_barrier(0)
; template <class Epi, bool ALIGN_EPI = true, bool SP2 = true>
; DI void gemm_phase(LAS unsigned char* lds, const Gemm g, const StaticOrder& S, const Epi& E) {
;     ...
;             PG8_LDA(At, 0, 1); PG8_STAGE(PG8_SB(0, 0), b2, voffB); PG8_STAGE(PG8_SB(0, 1), b2 + hstep, voffB); PG8_STAGE(PG8_SA(0, 0), a2, voffA);
;             PG8_WAIT_V(8); PG8_WAIT_L(0); PG8_BAR; PG8_MMA(1, 0, At, B0); PG8_MMA(1, 1, At, B1); PG8_BAR; PG8_SCHED;
;             PG8_LDB(B0, 1, 0); PG8_LDB(B1, 1, 1); PG8_SCHED; PG8_LDA(At, 1, 0); PG8_STAGE(PG8_SA(0, 1), a2 + hstepA, voffA);
	s_mov_b64 s[16:17], s[44:45]
	v_mov_b32_e32 v134, v129
	s_mov_b32 m0, s86
	s_nop 1
	ds_read_b128 v[36:39], v133 offset:16384
	ds_read_b128 v[44:47], v133 offset:17408
	ds_read_b128 v[204:207], v133 offset:18432
	ds_read_b128 v[208:211], v133 offset:19456
	ds_read_b128 v[212:215], v133 offset:20480
	ds_read_b128 v[216:219], v133 offset:21504
	ds_read_b128 v[220:223], v133 offset:22528
	ds_read_b128 v[224:227], v133 offset:23552
	s_nop 0
	global_load_lds_dwordx4 v134, s[16:17]
	v_mov_b32_e32 v134, v131
	s_mov_b32 m0, s15
	s_nop 0
	global_load_lds_dwordx4 v134, s[16:17]
	s_add_u32 s16, s44, 0x10000
	s_addc_u32 s17, s45, 0
	v_mov_b32_e32 v134, v129
	s_mov_b32 m0, s42
	s_nop 0
	global_load_lds_dwordx4 v134, s[16:17]
	v_mov_b32_e32 v134, v131
	s_mov_b32 m0, s43
	s_nop 0
	global_load_lds_dwordx4 v134, s[16:17]
	s_mov_b64 s[16:17], s[48:49]
	v_mov_b32_e32 v134, v128
	s_mov_b32 m0, s54
	s_nop 0
	global_load_lds_dwordx4 v134, s[16:17]
	v_mov_b32_e32 v134, v130
	s_mov_b32 m0, s55
	s_nop 0
	global_load_lds_dwordx4 v134, s[16:17]
	s_waitcnt vmcnt(8)
	s_waitcnt lgkmcnt(0)
	s_barrier
	s_setprio 1
	s_waitcnt lgkmcnt(0)
	v_mfma_f32_16x16x32_bf16 v[0:3], v[104:107], v[220:223], v[0:3]
	v_mfma_f32_16x16x32_bf16 v[4:7], v[112:115], v[220:223], v[4:7]
	v_mfma_f32_16x16x32_bf16 v[148:151], v[104:107], v[36:39], v[148:151]
	v_mfma_f32_16x16x32_bf16 v[152:155], v[112:115], v[36:39], v[152:155]
	v_mfma_f32_16x16x32_bf16 v[156:159], v[104:107], v[204:207], v[156:159]
	v_mfma_f32_16x16x32_bf16 v[176:179], v[112:115], v[204:207], v[176:179]
	v_mfma_f32_16x16x32_bf16 v[180:183], v[104:107], v[212:215], v[180:183]
	v_mfma_f32_16x16x32_bf16 v[184:187], v[112:115], v[212:215], v[184:187]
	v_mfma_f32_16x16x32_bf16 v[0:3], v[108:111], v[224:227], v[0:3]
	v_mfma_f32_16x16x32_bf16 v[4:7], v[116:119], v[224:227], v[4:7]
	v_mfma_f32_16x16x32_bf16 v[148:151], v[108:111], v[44:47], v[148:151]
	v_mfma_f32_16x16x32_bf16 v[152:155], v[116:119], v[44:47], v[152:155]
	v_mfma_f32_16x16x32_bf16 v[156:159], v[108:111], v[208:211], v[156:159]
	v_mfma_f32_16x16x32_bf16 v[176:179], v[116:119], v[208:211], v[176:179]
	v_mfma_f32_16x16x32_bf16 v[180:183], v[108:111], v[216:219], v[180:183]
	v_mfma_f32_16x16x32_bf16 v[184:187], v[116:119], v[216:219], v[184:187]
	v_mfma_f32_16x16x32_bf16 v[8:11], v[120:123], v[36:39], v[8:11]
	v_mfma_f32_16x16x32_bf16 v[228:231], v[124:127], v[44:47], v[8:11]
	v_mfma_f32_16x16x32_bf16 v[8:11], v[188:191], v[36:39], v[12:15]
	v_mfma_f32_16x16x32_bf16 v[232:235], v[192:195], v[44:47], v[8:11]
	v_mfma_f32_16x16x32_bf16 v[8:11], v[120:123], v[204:207], v[24:27]
	v_mfma_f32_16x16x32_bf16 v[236:239], v[124:127], v[208:211], v[8:11]
	v_mfma_f32_16x16x32_bf16 v[8:11], v[188:191], v[204:207], v[28:31]
	v_mfma_f32_16x16x32_bf16 v[204:207], v[192:195], v[208:211], v[8:11]
	v_mfma_f32_16x16x32_bf16 v[8:11], v[120:123], v[212:215], v[60:63]
	v_mfma_f32_16x16x32_bf16 v[208:211], v[124:127], v[216:219], v[8:11]
	v_mfma_f32_16x16x32_bf16 v[8:11], v[188:191], v[212:215], v[100:103]
	v_mfma_f32_16x16x32_bf16 v[212:215], v[192:195], v[216:219], v[8:11]
	v_mfma_f32_16x16x32_bf16 v[8:11], v[120:123], v[220:223], v[16:19]
	v_mfma_f32_16x16x32_bf16 v[216:219], v[124:127], v[224:227], v[8:11]
	v_mfma_f32_16x16x32_bf16 v[8:11], v[188:191], v[220:223], v[20:23]
	v_mfma_f32_16x16x32_bf16 v[188:191], v[192:195], v[224:227], v[8:11]
	s_setprio 0
	s_barrier
	s_nop 4
	ds_read_b128 v[8:11], v136
	ds_read_b128 v[12:15], v136 offset:1024
	ds_read_b128 v[16:19], v136 offset:2048
	ds_read_b128 v[20:23], v136 offset:3072
	ds_read_b128 v[192:195], v138
	ds_read_b128 v[220:223], v138 offset:1024
	ds_read_b128 v[224:227], v138 offset:2048
	ds_read_b128 v[240:243], v138 offset:3072
	s_add_u32 s16, s48, 0x10000
	s_addc_u32 s17, s49, 0
	v_mov_b32_e32 v36, v128
	s_mov_b32 m0, s69
	ds_read_b128 v[24:27], v133 offset:32768
	ds_read_b128 v[28:31], v133 offset:33792
	ds_read_b128 v[60:63], v133 offset:34816
	ds_read_b128 v[244:247], v133 offset:35840
	ds_read_b128 v[248:251], v133 offset:36864
	ds_read_b128 v[144:147], v133 offset:37888
	ds_read_b128 v[138:141], v133 offset:38912
	ds_read_b128 v[172:175], v133 offset:39936
	s_nop 0
	global_load_lds_dwordx4 v36, s[16:17]
	v_mov_b32_e32 v36, v130
	s_mov_b32 m0, s70
	s_nop 0
	global_load_lds_dwordx4 v36, s[16:17]
	s_waitcnt vmcnt(8)
	s_waitcnt lgkmcnt(0)
	s_barrier
; #define PG8_LDA(dst, b, h) do { _Pragma("unroll") for (int m = 0; m < 4; ++m) _Pragma("unroll") for (int k = 0; k < 2; ++k) dst[m][k] = *(const LAS bf16x8*)(lds + PG8_SA(b, h) + aoff + m * 2048 + k * 1024); } while (0)
; #define PG8_MMA(ai, bj, At, Bt) do { __builtin_amdgcn_s_setprio(1); _Pragma("unroll") for (int m = 0; m < 4; ++m) _Pragma("unroll") for (int n = 0; n < 2; ++n) _Pragma("unroll") for (int k = 0; k < 2; ++k) \
;         acc[ai][bj][m][n] = __builtin_amdgcn_mfma_f32_16x16x32_bf16(Bt[n][k], At[m][k], acc[ai][bj][m][n], 0, 0, 0); __builtin_amdgcn_s_setprio(0); } while (0)
; #define PG8_WAIT_V(n) asm volatile("s_waitcnt vmcnt(" #n ")" ::: "memory")
; #define PG8_WAIT_L(n) asm volatile("s_waitcnt lgkmcnt(" #n ")" ::: "memory")
; #define PG8_BAR __builtin_amdgcn_s_barrier()
; #define PG8_SCHED __builtin_amdgcn_sched_barrier(0)
; template <class Epi, bool ALIGN_EPI = true, bool SP2 = true>
; DI void gemm_phase(LAS unsigned char* lds, const Gemm g, const StaticOrder& S, const Epi& E) {
;     ...
;             PG8_WAIT_V(8); PG8_WAIT_L(0); PG8_BAR; PG8_MMA(0, 0, At, B0); PG8_MMA(0, 1, At, B1); PG8_BAR; PG8_SCHED;
;             PG8_LDA(At, 1, 1); PG8_STAGE(PG8_SB(1, 0), b3, voffB); PG8_STAGE(PG8_SB(1, 1), b3 + hstep, voffB); PG8_STAGE(PG8_SA(1, 0), a3, voffA);
;             PG8_WAIT_V(8); PG8_WAIT_L(0); PG8_BAR; PG8_MMA(1, 0, At, B0); PG8_MMA(1, 1, At, B1); PG8_BAR; PG8_SCHED;
;     ...
;         if constexpr (ALIGN_EPI) { if (wr == 0) PG8_BAR; }
	s_setprio 1
	s_waitcnt lgkmcnt(0)
	v_mfma_f32_16x16x32_bf16 v[36:39], v[8:11], v[24:27], v[64:67]
	v_mfma_f32_16x16x32_bf16 v[124:127], v[12:15], v[28:31], v[36:39]
	v_mfma_f32_16x16x32_bf16 v[36:39], v[16:19], v[24:27], v[68:71]
	v_mfma_f32_16x16x32_bf16 v[116:119], v[20:23], v[28:31], v[36:39]
	v_mfma_f32_16x16x32_bf16 v[36:39], v[8:11], v[60:63], v[72:75]
	v_mfma_f32_16x16x32_bf16 v[108:111], v[12:15], v[244:247], v[36:39]
	v_mfma_f32_16x16x32_bf16 v[36:39], v[16:19], v[60:63], v[76:79]
	v_mfma_f32_16x16x32_bf16 v[100:103], v[20:23], v[244:247], v[36:39]
	v_mfma_f32_16x16x32_bf16 v[36:39], v[8:11], v[248:251], v[80:83]
	v_mfma_f32_16x16x32_bf16 v[76:79], v[12:15], v[144:147], v[36:39]
	v_mfma_f32_16x16x32_bf16 v[36:39], v[16:19], v[248:251], v[84:87]
	v_mfma_f32_16x16x32_bf16 v[68:71], v[20:23], v[144:147], v[36:39]
	v_mfma_f32_16x16x32_bf16 v[36:39], v[8:11], v[138:141], v[88:91]
	v_mfma_f32_16x16x32_bf16 v[44:47], v[12:15], v[172:175], v[36:39]
	v_mfma_f32_16x16x32_bf16 v[36:39], v[16:19], v[138:141], v[92:95]
	v_mfma_f32_16x16x32_bf16 v[36:39], v[20:23], v[172:175], v[36:39]
	v_mfma_f32_16x16x32_bf16 v[64:67], v[192:195], v[24:27], v[96:99]
	v_mfma_f32_16x16x32_bf16 v[24:27], v[224:227], v[24:27], v[32:35]
	v_mfma_f32_16x16x32_bf16 v[112:115], v[240:243], v[28:31], v[24:27]
	v_mfma_f32_16x16x32_bf16 v[24:27], v[192:195], v[60:63], v[196:199]
	v_mfma_f32_16x16x32_bf16 v[104:107], v[220:223], v[244:247], v[24:27]
	v_mfma_f32_16x16x32_bf16 v[24:27], v[224:227], v[60:63], v[40:43]
	v_mfma_f32_16x16x32_bf16 v[96:99], v[240:243], v[244:247], v[24:27]
	v_mfma_f32_16x16x32_bf16 v[24:27], v[192:195], v[248:251], v[200:203]
	v_mfma_f32_16x16x32_bf16 v[72:75], v[220:223], v[144:147], v[24:27]
	v_mfma_f32_16x16x32_bf16 v[24:27], v[224:227], v[248:251], v[48:51]
	v_mfma_f32_16x16x32_bf16 v[120:123], v[220:223], v[28:31], v[64:67]
	v_mfma_f32_16x16x32_bf16 v[64:67], v[240:243], v[144:147], v[24:27]
	v_mfma_f32_16x16x32_bf16 v[24:27], v[192:195], v[138:141], v[52:55]
	v_mfma_f32_16x16x32_bf16 v[40:43], v[220:223], v[172:175], v[24:27]
	v_mfma_f32_16x16x32_bf16 v[24:27], v[224:227], v[138:141], v[56:59]
	v_mfma_f32_16x16x32_bf16 v[32:35], v[240:243], v[172:175], v[24:27]
	s_setprio 0
	s_barrier
	s_add_u32 s16, s44, 0x80
	s_addc_u32 s17, s45, 0
	s_nop 2
	v_mov_b32_e32 v24, v129
	s_mov_b32 m0, s96
	ds_read_b128 v[48:51], v133 offset:49152
	ds_read_b128 v[52:55], v133 offset:50176
	ds_read_b128 v[138:141], v133 offset:51200
	ds_read_b128 v[144:147], v133 offset:52224
	ds_read_b128 v[172:175], v133 offset:53248
	ds_read_b128 v[196:199], v133 offset:54272
	ds_read_b128 v[200:203], v133 offset:55296
	ds_read_b128 v[244:247], v133 offset:56320
	s_nop 0
	global_load_lds_dwordx4 v24, s[16:17]
	v_mov_b32_e32 v24, v131
	s_mov_b32 m0, s8
	s_nop 0
	global_load_lds_dwordx4 v24, s[16:17]
	s_add_u32 s16, s44, 0x10080
	s_addc_u32 s17, s45, 0
	v_mov_b32_e32 v24, v129
	s_mov_b32 m0, s9
	s_nop 0
	global_load_lds_dwordx4 v24, s[16:17]
	v_mov_b32_e32 v24, v131
	s_mov_b32 m0, s46
	s_nop 0
	global_load_lds_dwordx4 v24, s[16:17]
	v_mov_b32_e32 v24, v128
	s_mov_b32 m0, s73
	s_nop 0
	global_load_lds_dwordx4 v24, s[6:7]
	v_mov_b32_e32 v24, v130
	s_mov_b32 m0, s81
	s_nop 0
	global_load_lds_dwordx4 v24, s[6:7]
	s_waitcnt vmcnt(8)
	s_waitcnt lgkmcnt(0)
	s_barrier
	s_setprio 1
	s_waitcnt lgkmcnt(0)
	v_mfma_f32_16x16x32_bf16 v[24:27], v[8:11], v[48:51], v[148:151]
	v_mfma_f32_16x16x32_bf16 v[92:95], v[12:15], v[52:55], v[24:27]
	v_mfma_f32_16x16x32_bf16 v[24:27], v[16:19], v[48:51], v[152:155]
	v_mfma_f32_16x16x32_bf16 v[88:91], v[20:23], v[52:55], v[24:27]
	v_mfma_f32_16x16x32_bf16 v[24:27], v[8:11], v[138:141], v[156:159]
	v_mfma_f32_16x16x32_bf16 v[60:63], v[12:15], v[144:147], v[24:27]
	v_mfma_f32_16x16x32_bf16 v[24:27], v[16:19], v[138:141], v[176:179]
	v_mfma_f32_16x16x32_bf16 v[56:59], v[20:23], v[144:147], v[24:27]
	v_mfma_f32_16x16x32_bf16 v[24:27], v[8:11], v[172:175], v[180:183]
	v_mfma_f32_16x16x32_bf16 v[0:3], v[8:11], v[200:203], v[0:3]
	v_mfma_f32_16x16x32_bf16 v[28:31], v[12:15], v[196:199], v[24:27]
	v_mfma_f32_16x16x32_bf16 v[24:27], v[16:19], v[172:175], v[184:187]
	v_mfma_f32_16x16x32_bf16 v[12:15], v[12:15], v[244:247], v[0:3]
	v_mfma_f32_16x16x32_bf16 v[0:3], v[16:19], v[200:203], v[4:7]
	v_mfma_f32_16x16x32_bf16 v[24:27], v[20:23], v[196:199], v[24:27]
	v_mfma_f32_16x16x32_bf16 v[8:11], v[20:23], v[244:247], v[0:3]
	v_mfma_f32_16x16x32_bf16 v[0:3], v[192:195], v[48:51], v[228:231]
	v_mfma_f32_16x16x32_bf16 v[84:87], v[220:223], v[52:55], v[0:3]
	v_mfma_f32_16x16x32_bf16 v[0:3], v[224:227], v[48:51], v[232:235]
	v_mfma_f32_16x16x32_bf16 v[80:83], v[240:243], v[52:55], v[0:3]
	v_mfma_f32_16x16x32_bf16 v[0:3], v[192:195], v[138:141], v[236:239]
	v_mfma_f32_16x16x32_bf16 v[52:55], v[220:223], v[144:147], v[0:3]
	v_mfma_f32_16x16x32_bf16 v[0:3], v[224:227], v[138:141], v[204:207]
	v_mfma_f32_16x16x32_bf16 v[48:51], v[240:243], v[144:147], v[0:3]
	v_mfma_f32_16x16x32_bf16 v[0:3], v[192:195], v[172:175], v[208:211]
	v_mfma_f32_16x16x32_bf16 v[20:23], v[220:223], v[196:199], v[0:3]
	v_mfma_f32_16x16x32_bf16 v[0:3], v[224:227], v[172:175], v[212:215]
	v_mfma_f32_16x16x32_bf16 v[16:19], v[240:243], v[196:199], v[0:3]
	v_mfma_f32_16x16x32_bf16 v[0:3], v[192:195], v[200:203], v[216:219]
	v_mfma_f32_16x16x32_bf16 v[4:7], v[220:223], v[244:247], v[0:3]
	v_mfma_f32_16x16x32_bf16 v[0:3], v[224:227], v[200:203], v[188:191]
	v_mfma_f32_16x16x32_bf16 v[0:3], v[240:243], v[244:247], v[0:3]
	s_setprio 0
	s_barrier
	s_andn2_b64 vcc, exec, s[76:77]
	s_cbranch_vccnz .LBB0_558
	s_barrier

; #define PG8_LDA(dst, b, h) do { _Pragma("unroll") for (int m = 0; m < 4; ++m) _Pragma("unroll") for (int k = 0; k < 2; ++k) dst[m][k] = *(const LAS bf16x8*)(lds + PG8_SA(b, h) + aoff + m * 2048 + k * 1024); } while (0)
; #define PG8_LDB(dst, b, h) do { _Pragma("unroll") for (int n = 0; n < 2; ++n) _Pragma("unroll") for (int k = 0; k < 2; ++k) dst[n][k] = *(const LAS bf16x8*)(lds + PG8_SB(b, h) + boff + n * 2048 + k * 1024); } while (0)
; #define PG8_MMA(ai, bj, At, Bt) do { __builtin_amdgcn_s_setprio(1); _Pragma("unroll") for (int m = 0; m < 4; ++m) _Pragma("unroll") for (int n = 0; n < 2; ++n) _Pragma("unroll") for (int k = 0; k < 2; ++k) \
;         acc[ai][bj][m][n] = __builtin_amdgcn_mfma_f32_16x16x32_bf16(Bt[n][k], At[m][k], acc[ai][bj][m][n], 0, 0, 0); __builtin_amdgcn_s_setprio(0); } while (0)
; #define PG8_WAIT_V(n) asm volatile("s_waitcnt vmcnt(" #n ")" ::: "memory")
; #define PG8_WAIT_L(n) asm volatile("s_waitcnt lgkmcnt(" #n ")" ::: "memory")
; #define PG8_BAR __builtin_amdgcn_s_barrier()
; #define PG8_SCHED __builtin_amdgcn_sched_barrier(0)
; template <class Epi, bool ALIGN_EPI = true, bool SP2 = true>
; DI void gemm_phase(LAS unsigned char* lds, const Gemm g, const StaticOrder& S, const Epi& E) {
;     ...
;             const bool last = (t == nt - 2);
;             const char* a1 = cA + (size_t)(t + 1) * kstep;
;             const char* a2 = last ? nA : cA + (size_t)(t + 2) * kstep; const char* b2 = last ? nB : cB + (size_t)(t + 2) * kstep;
;             const char* a3 = a2 + kstep; const char* b3 = b2 + kstep;
;             if constexpr (SP2) {
;             PG8_LDB(B0, 0, 0); PG8_LDB(B1, 0, 1); PG8_SCHED; PG8_LDA(At, 0, 0); PG8_STAGE(PG8_SA(1, 1), a1 + hstepA, voffA);
;             PG8_WAIT_V(8); PG8_WAIT_L(0); PG8_BAR; PG8_MMA(0, 0, At, B0); PG8_MMA(0, 1, At, B1); PG8_BAR; PG8_SCHED;
;             PG8_LDA(At, 0, 1); PG8_STAGE(PG8_SB(0, 0), b2, voffB); PG8_STAGE(PG8_SB(0, 1), b2 + hstep, voffB); PG8_STAGE(PG8_SA(0, 0), a2, voffA);
.LBB0_591:
	s_add_u32 s6, s4, 0xfffc0080
	s_addc_u32 s7, s5, -1
	s_cmp_eq_u32 s81, 12
	s_cselect_b32 s48, s36, s6
	s_cselect_b32 s49, s19, s7
	s_cselect_b32 s40, s38, s70
	s_cselect_b32 s41, s17, s72
	s_add_u32 s6, s48, 0x80
	s_addc_u32 s7, s49, 0
	s_add_i32 s96, 0, 0x10000
	s_add_i32 s97, 0, 0x14000
	v_add_u32_e32 v144, s96, v152
	v_add_u32_e32 v148, s97, v152
	ds_read_b128 v[128:131], v144
	ds_read_b128 v[132:135], v144 offset:1024
	ds_read_b128 v[138:141], v144 offset:2048
	ds_read_b128 v[144:147], v144 offset:3072
	ds_read_b128 v[154:157], v148
	ds_read_b128 v[158:161], v148 offset:1024
	ds_read_b128 v[172:175], v148 offset:2048
	ds_read_b128 v[176:179], v148 offset:3072
	s_mov_b64 s[94:95], s[4:5]
	v_mov_b32_e32 v148, v136
	ds_read_b128 v[180:183], v153
	ds_read_b128 v[184:187], v153 offset:1024
	ds_read_b128 v[188:191], v153 offset:2048
	ds_read_b128 v[192:195], v153 offset:3072
	ds_read_b128 v[196:199], v153 offset:4096
	ds_read_b128 v[200:203], v153 offset:5120
	ds_read_b128 v[204:207], v153 offset:6144
	ds_read_b128 v[208:211], v153 offset:7168
	s_add_i32 m0, s92, 0xc000
	s_nop 0
	global_load_lds_dwordx4 v148, s[94:95]
	v_mov_b32_e32 v148, v150
	s_add_i32 m0, s92, 0xe000
	s_nop 0
	global_load_lds_dwordx4 v148, s[94:95]
	s_waitcnt vmcnt(8)
	s_waitcnt lgkmcnt(0)
	s_barrier
	s_setprio 1
	s_waitcnt lgkmcnt(0)
	v_mfma_f32_16x16x32_bf16 v[124:127], v[128:131], v[180:183], v[124:127]
	v_mfma_f32_16x16x32_bf16 v[120:123], v[138:141], v[180:183], v[120:123]
	v_mfma_f32_16x16x32_bf16 v[108:111], v[128:131], v[188:191], v[108:111]
	v_mfma_f32_16x16x32_bf16 v[104:107], v[138:141], v[188:191], v[104:107]
	v_mfma_f32_16x16x32_bf16 v[92:95], v[128:131], v[196:199], v[92:95]
	v_mfma_f32_16x16x32_bf16 v[88:91], v[138:141], v[196:199], v[88:91]
	v_mfma_f32_16x16x32_bf16 v[76:79], v[128:131], v[204:207], v[76:79]
	v_mfma_f32_16x16x32_bf16 v[72:75], v[138:141], v[204:207], v[72:75]
	v_mfma_f32_16x16x32_bf16 v[124:127], v[132:135], v[184:187], v[124:127]
	v_mfma_f32_16x16x32_bf16 v[120:123], v[144:147], v[184:187], v[120:123]
	v_mfma_f32_16x16x32_bf16 v[108:111], v[132:135], v[192:195], v[108:111]
	v_mfma_f32_16x16x32_bf16 v[104:107], v[144:147], v[192:195], v[104:107]
	v_mfma_f32_16x16x32_bf16 v[92:95], v[132:135], v[200:203], v[92:95]
	v_mfma_f32_16x16x32_bf16 v[88:91], v[144:147], v[200:203], v[88:91]
	v_mfma_f32_16x16x32_bf16 v[76:79], v[132:135], v[208:211], v[76:79]
	v_mfma_f32_16x16x32_bf16 v[72:75], v[144:147], v[208:211], v[72:75]
	v_mfma_f32_16x16x32_bf16 v[116:119], v[154:157], v[180:183], v[116:119]
	v_mfma_f32_16x16x32_bf16 v[112:115], v[172:175], v[180:183], v[112:115]
	v_mfma_f32_16x16x32_bf16 v[100:103], v[154:157], v[188:191], v[100:103]
	v_mfma_f32_16x16x32_bf16 v[96:99], v[172:175], v[188:191], v[96:99]
	v_mfma_f32_16x16x32_bf16 v[84:87], v[154:157], v[196:199], v[84:87]
	v_mfma_f32_16x16x32_bf16 v[80:83], v[172:175], v[196:199], v[80:83]
	v_mfma_f32_16x16x32_bf16 v[68:71], v[154:157], v[204:207], v[68:71]
	v_mfma_f32_16x16x32_bf16 v[64:67], v[172:175], v[204:207], v[64:67]
	v_mfma_f32_16x16x32_bf16 v[116:119], v[158:161], v[184:187], v[116:119]
	v_mfma_f32_16x16x32_bf16 v[112:115], v[176:179], v[184:187], v[112:115]
	v_mfma_f32_16x16x32_bf16 v[100:103], v[158:161], v[192:195], v[100:103]
	v_mfma_f32_16x16x32_bf16 v[96:99], v[176:179], v[192:195], v[96:99]
	v_mfma_f32_16x16x32_bf16 v[84:87], v[158:161], v[200:203], v[84:87]
	v_mfma_f32_16x16x32_bf16 v[80:83], v[176:179], v[200:203], v[80:83]
	v_mfma_f32_16x16x32_bf16 v[68:71], v[158:161], v[208:211], v[68:71]
	v_mfma_f32_16x16x32_bf16 v[64:67], v[176:179], v[208:211], v[64:67]
	s_setprio 0
	s_barrier
	s_mov_b64 s[94:95], s[40:41]
	v_mov_b32_e32 v148, v143
	s_add_i32 s96, s96, s69
	ds_read_b128 v[180:183], v153 offset:16384
	ds_read_b128 v[184:187], v153 offset:17408
	ds_read_b128 v[188:191], v153 offset:18432
	ds_read_b128 v[192:195], v153 offset:19456
	ds_read_b128 v[196:199], v153 offset:20480
	ds_read_b128 v[200:203], v153 offset:21504
	ds_read_b128 v[204:207], v153 offset:22528
	ds_read_b128 v[208:211], v153 offset:23552
	s_mov_b32 m0, s96
	s_nop 0
	global_load_lds_dwordx4 v148, s[94:95]
	v_mov_b32_e32 v148, v151
	s_add_i32 m0, s96, 0x2000
	s_nop 0
	global_load_lds_dwordx4 v148, s[94:95]
	s_add_u32 s94, s40, 0x40000
	s_addc_u32 s95, s41, 0
	v_mov_b32_e32 v148, v143
	s_add_i32 s96, s97, s69
	s_mov_b32 m0, s96
	s_nop 0
	global_load_lds_dwordx4 v148, s[94:95]
	v_mov_b32_e32 v148, v151
	s_add_i32 m0, s96, 0x2000
	s_nop 0
	global_load_lds_dwordx4 v148, s[94:95]
	s_mov_b64 s[94:95], s[48:49]
	v_mov_b32_e32 v148, v136
	s_mov_b32 m0, s92
	s_nop 0
	global_load_lds_dwordx4 v148, s[94:95]
	v_mov_b32_e32 v148, v150
	s_mov_b32 m0, s73
	s_nop 0
	global_load_lds_dwordx4 v148, s[94:95]
	s_waitcnt vmcnt(8)
	s_waitcnt lgkmcnt(0)
	s_barrier
; #define PG8_LDA(dst, b, h) do { _Pragma("unroll") for (int m = 0; m < 4; ++m) _Pragma("unroll") for (int k = 0; k < 2; ++k) dst[m][k] = *(const LAS bf16x8*)(lds + PG8_SA(b, h) + aoff + m * 2048 + k * 1024); } while (0)
; #define PG8_LDB(dst, b, h) do { _Pragma("unroll") for (int n = 0; n < 2; ++n) _Pragma("unroll") for (int k = 0; k < 2; ++k) dst[n][k] = *(const LAS bf16x8*)(lds + PG8_SB(b, h) + boff + n * 2048 + k * 1024); } while (0)
; #define PG8_MMA(ai, bj, At, Bt) do { __builtin_amdgcn_s_setprio(1); _Pragma("unroll") for (int m = 0; m < 4; ++m) _Pragma("unroll") for (int n = 0; n < 2; ++n) _Pragma("unroll") for (int k = 0; k < 2; ++k) \
;         acc[ai][bj][m][n] = __builtin_amdgcn_mfma_f32_16x16x32_bf16(Bt[n][k], At[m][k], acc[ai][bj][m][n], 0, 0, 0); __builtin_amdgcn_s_setprio(0); } while (0)
; #define PG8_WAIT_V(n) asm volatile("s_waitcnt vmcnt(" #n ")" ::: "memory")
; #define PG8_WAIT_L(n) asm volatile("s_waitcnt lgkmcnt(" #n ")" ::: "memory")
; #define PG8_BAR __builtin_amdgcn_s_barrier()
; #define PG8_SCHED __builtin_amdgcn_sched_barrier(0)
; template <class Epi, bool ALIGN_EPI = true, bool SP2 = true>
; DI void gemm_phase(LAS unsigned char* lds, const Gemm g, const StaticOrder& S, const Epi& E) {
;     ...
;             PG8_WAIT_V(8); PG8_WAIT_L(0); PG8_BAR; PG8_MMA(1, 0, At, B0); PG8_MMA(1, 1, At, B1); PG8_BAR; PG8_SCHED;
;             PG8_LDB(B0, 1, 0); PG8_LDB(B1, 1, 1); PG8_SCHED; PG8_LDA(At, 1, 0); PG8_STAGE(PG8_SA(0, 1), a2 + hstepA, voffA);
;             PG8_WAIT_V(8); PG8_WAIT_L(0); PG8_BAR; PG8_MMA(0, 0, At, B0); PG8_MMA(0, 1, At, B1); PG8_BAR; PG8_SCHED;
	s_setprio 1
	s_waitcnt lgkmcnt(0)
	v_mfma_f32_16x16x32_bf16 v[60:63], v[128:131], v[180:183], v[60:63]
	v_mfma_f32_16x16x32_bf16 v[56:59], v[138:141], v[180:183], v[56:59]
	v_mfma_f32_16x16x32_bf16 v[44:47], v[128:131], v[188:191], v[44:47]
	v_mfma_f32_16x16x32_bf16 v[40:43], v[138:141], v[188:191], v[40:43]
	v_mfma_f32_16x16x32_bf16 v[28:31], v[128:131], v[196:199], v[28:31]
	v_mfma_f32_16x16x32_bf16 v[24:27], v[138:141], v[196:199], v[24:27]
	v_mfma_f32_16x16x32_bf16 v[12:15], v[128:131], v[204:207], v[12:15]
	v_mfma_f32_16x16x32_bf16 v[8:11], v[138:141], v[204:207], v[8:11]
	v_mfma_f32_16x16x32_bf16 v[60:63], v[132:135], v[184:187], v[60:63]
	v_mfma_f32_16x16x32_bf16 v[56:59], v[144:147], v[184:187], v[56:59]
	v_mfma_f32_16x16x32_bf16 v[44:47], v[132:135], v[192:195], v[44:47]
	v_mfma_f32_16x16x32_bf16 v[40:43], v[144:147], v[192:195], v[40:43]
	v_mfma_f32_16x16x32_bf16 v[28:31], v[132:135], v[200:203], v[28:31]
	v_mfma_f32_16x16x32_bf16 v[24:27], v[144:147], v[200:203], v[24:27]
	v_mfma_f32_16x16x32_bf16 v[12:15], v[132:135], v[208:211], v[12:15]
	v_mfma_f32_16x16x32_bf16 v[8:11], v[144:147], v[208:211], v[8:11]
	v_mfma_f32_16x16x32_bf16 v[52:55], v[154:157], v[180:183], v[52:55]
	v_mfma_f32_16x16x32_bf16 v[48:51], v[172:175], v[180:183], v[48:51]
	v_mfma_f32_16x16x32_bf16 v[36:39], v[154:157], v[188:191], v[36:39]
	v_mfma_f32_16x16x32_bf16 v[32:35], v[172:175], v[188:191], v[32:35]
	v_mfma_f32_16x16x32_bf16 v[20:23], v[154:157], v[196:199], v[20:23]
	v_mfma_f32_16x16x32_bf16 v[16:19], v[172:175], v[196:199], v[16:19]
	v_mfma_f32_16x16x32_bf16 v[4:7], v[154:157], v[204:207], v[4:7]
	v_mfma_f32_16x16x32_bf16 v[0:3], v[172:175], v[204:207], v[0:3]
	v_mfma_f32_16x16x32_bf16 v[52:55], v[158:161], v[184:187], v[52:55]
	v_mfma_f32_16x16x32_bf16 v[48:51], v[176:179], v[184:187], v[48:51]
	v_mfma_f32_16x16x32_bf16 v[36:39], v[158:161], v[192:195], v[36:39]
	v_mfma_f32_16x16x32_bf16 v[32:35], v[176:179], v[192:195], v[32:35]
	v_mfma_f32_16x16x32_bf16 v[20:23], v[158:161], v[200:203], v[20:23]
	v_mfma_f32_16x16x32_bf16 v[16:19], v[176:179], v[200:203], v[16:19]
	v_mfma_f32_16x16x32_bf16 v[4:7], v[158:161], v[208:211], v[4:7]
	v_mfma_f32_16x16x32_bf16 v[0:3], v[176:179], v[208:211], v[0:3]
	s_setprio 0
	s_barrier
	s_add_i32 s94, 0, 0x18000
	s_add_i32 s95, 0, 0x1c000
	v_add_u32_e32 v144, s94, v152
	v_add_u32_e32 v148, s95, v152
	ds_read_b128 v[128:131], v144
	ds_read_b128 v[132:135], v144 offset:1024
	ds_read_b128 v[138:141], v144 offset:2048
	ds_read_b128 v[144:147], v144 offset:3072
	ds_read_b128 v[154:157], v148
	ds_read_b128 v[158:161], v148 offset:1024
	ds_read_b128 v[172:175], v148 offset:2048
	ds_read_b128 v[176:179], v148 offset:3072
	s_add_u32 s48, s48, 0x40000
	s_addc_u32 s49, s49, 0
	v_mov_b32_e32 v148, v136
	s_mov_b32 m0, s0
	ds_read_b128 v[180:183], v153 offset:32768
	ds_read_b128 v[184:187], v153 offset:33792
	ds_read_b128 v[188:191], v153 offset:34816
	ds_read_b128 v[192:195], v153 offset:35840
	ds_read_b128 v[196:199], v153 offset:36864
	ds_read_b128 v[200:203], v153 offset:37888
	ds_read_b128 v[204:207], v153 offset:38912
	ds_read_b128 v[208:211], v153 offset:39936
	s_nop 0
	global_load_lds_dwordx4 v148, s[48:49]
	v_mov_b32_e32 v148, v150
	s_mov_b32 m0, s1
	s_nop 0
	global_load_lds_dwordx4 v148, s[48:49]
	s_waitcnt vmcnt(8)
	s_waitcnt lgkmcnt(0)
	s_barrier
	s_setprio 1
	s_waitcnt lgkmcnt(0)
	v_mfma_f32_16x16x32_bf16 v[124:127], v[128:131], v[180:183], v[124:127]
	v_mfma_f32_16x16x32_bf16 v[120:123], v[138:141], v[180:183], v[120:123]
	v_mfma_f32_16x16x32_bf16 v[108:111], v[128:131], v[188:191], v[108:111]
	v_mfma_f32_16x16x32_bf16 v[104:107], v[138:141], v[188:191], v[104:107]
	v_mfma_f32_16x16x32_bf16 v[92:95], v[128:131], v[196:199], v[92:95]
	v_mfma_f32_16x16x32_bf16 v[88:91], v[138:141], v[196:199], v[88:91]
	v_mfma_f32_16x16x32_bf16 v[76:79], v[128:131], v[204:207], v[76:79]
	v_mfma_f32_16x16x32_bf16 v[72:75], v[138:141], v[204:207], v[72:75]
	v_mfma_f32_16x16x32_bf16 v[124:127], v[132:135], v[184:187], v[124:127]
	v_mfma_f32_16x16x32_bf16 v[120:123], v[144:147], v[184:187], v[120:123]
	v_mfma_f32_16x16x32_bf16 v[108:111], v[132:135], v[192:195], v[108:111]
	v_mfma_f32_16x16x32_bf16 v[104:107], v[144:147], v[192:195], v[104:107]
	v_mfma_f32_16x16x32_bf16 v[92:95], v[132:135], v[200:203], v[92:95]
	v_mfma_f32_16x16x32_bf16 v[88:91], v[144:147], v[200:203], v[88:91]
	v_mfma_f32_16x16x32_bf16 v[76:79], v[132:135], v[208:211], v[76:79]
	v_mfma_f32_16x16x32_bf16 v[72:75], v[144:147], v[208:211], v[72:75]
	v_mfma_f32_16x16x32_bf16 v[116:119], v[154:157], v[180:183], v[116:119]
	v_mfma_f32_16x16x32_bf16 v[112:115], v[172:175], v[180:183], v[112:115]
	v_mfma_f32_16x16x32_bf16 v[100:103], v[154:157], v[188:191], v[100:103]
	v_mfma_f32_16x16x32_bf16 v[96:99], v[172:175], v[188:191], v[96:99]
	v_mfma_f32_16x16x32_bf16 v[84:87], v[154:157], v[196:199], v[84:87]
	v_mfma_f32_16x16x32_bf16 v[80:83], v[172:175], v[196:199], v[80:83]
	v_mfma_f32_16x16x32_bf16 v[68:71], v[154:157], v[204:207], v[68:71]
	v_mfma_f32_16x16x32_bf16 v[64:67], v[172:175], v[204:207], v[64:67]
	v_mfma_f32_16x16x32_bf16 v[116:119], v[158:161], v[184:187], v[116:119]
	v_mfma_f32_16x16x32_bf16 v[112:115], v[176:179], v[184:187], v[112:115]
	v_mfma_f32_16x16x32_bf16 v[100:103], v[158:161], v[192:195], v[100:103]
	v_mfma_f32_16x16x32_bf16 v[96:99], v[176:179], v[192:195], v[96:99]
	v_mfma_f32_16x16x32_bf16 v[84:87], v[158:161], v[200:203], v[84:87]
	v_mfma_f32_16x16x32_bf16 v[80:83], v[176:179], v[200:203], v[80:83]
	v_mfma_f32_16x16x32_bf16 v[68:71], v[158:161], v[208:211], v[68:71]
	v_mfma_f32_16x16x32_bf16 v[64:67], v[176:179], v[208:211], v[64:67]
	s_setprio 0
	s_barrier
; #define PG8_LDA(dst, b, h) do { _Pragma("unroll") for (int m = 0; m < 4; ++m) _Pragma("unroll") for (int k = 0; k < 2; ++k) dst[m][k] = *(const LAS bf16x8*)(lds + PG8_SA(b, h) + aoff + m * 2048 + k * 1024); } while (0)
; #define PG8_MMA(ai, bj, At, Bt) do { __builtin_amdgcn_s_setprio(1); _Pragma("unroll") for (int m = 0; m < 4; ++m) _Pragma("unroll") for (int n = 0; n < 2; ++n) _Pragma("unroll") for (int k = 0; k < 2; ++k) \
;         acc[ai][bj][m][n] = __builtin_amdgcn_mfma_f32_16x16x32_bf16(Bt[n][k], At[m][k], acc[ai][bj][m][n], 0, 0, 0); __builtin_amdgcn_s_setprio(0); } while (0)
; #define PG8_WAIT_V(n) asm volatile("s_waitcnt vmcnt(" #n ")" ::: "memory")
; #define PG8_WAIT_L(n) asm volatile("s_waitcnt lgkmcnt(" #n ")" ::: "memory")
; #define PG8_BAR __builtin_amdgcn_s_barrier()
; #define PG8_SCHED __builtin_amdgcn_sched_barrier(0)
; template <class Epi, bool ALIGN_EPI = true, bool SP2 = true>
; DI void gemm_phase(LAS unsigned char* lds, const Gemm g, const StaticOrder& S, const Epi& E) {
;     ...
;             PG8_LDA(At, 1, 1); PG8_STAGE(PG8_SB(1, 0), b3, voffB); PG8_STAGE(PG8_SB(1, 1), b3 + hstep, voffB); PG8_STAGE(PG8_SA(1, 0), a3, voffA);
;             PG8_WAIT_V(8); PG8_WAIT_L(0); PG8_BAR; PG8_MMA(1, 0, At, B0); PG8_MMA(1, 1, At, B1); PG8_BAR; PG8_SCHED;
;     ...
;         if constexpr (ALIGN_EPI) { if (wr == 0) PG8_BAR; }
	s_add_u32 s48, s40, 0x80
	s_addc_u32 s49, s41, 0
	v_mov_b32_e32 v148, v143
	s_add_i32 s94, s94, s69
	ds_read_b128 v[180:183], v153 offset:49152
	ds_read_b128 v[184:187], v153 offset:50176
	ds_read_b128 v[188:191], v153 offset:51200
	ds_read_b128 v[192:195], v153 offset:52224
	ds_read_b128 v[196:199], v153 offset:53248
	ds_read_b128 v[200:203], v153 offset:54272
	ds_read_b128 v[204:207], v153 offset:55296
	ds_read_b128 v[208:211], v153 offset:56320
	s_mov_b32 m0, s94
	s_nop 0
	global_load_lds_dwordx4 v148, s[48:49]
	v_mov_b32_e32 v148, v151
	s_add_i32 m0, s94, 0x2000
	s_add_u32 s40, s40, 0x40080
	global_load_lds_dwordx4 v148, s[48:49]
	s_addc_u32 s41, s41, 0
	v_mov_b32_e32 v148, v143
	s_add_i32 s48, s95, s69
	s_mov_b32 m0, s48
	s_nop 0
	global_load_lds_dwordx4 v148, s[40:41]
	v_mov_b32_e32 v148, v151
	s_add_i32 m0, s48, 0x2000
	s_nop 0
	global_load_lds_dwordx4 v148, s[40:41]
	v_mov_b32_e32 v148, v136
	s_mov_b32 m0, s55
	s_nop 0
	global_load_lds_dwordx4 v148, s[6:7]
	v_mov_b32_e32 v148, v150
	s_mov_b32 m0, s83
	s_nop 0
	global_load_lds_dwordx4 v148, s[6:7]
	s_waitcnt vmcnt(8)
	s_waitcnt lgkmcnt(0)
	s_barrier
	s_setprio 1
	s_waitcnt lgkmcnt(0)
	v_mfma_f32_16x16x32_bf16 v[60:63], v[128:131], v[180:183], v[60:63]
	v_mfma_f32_16x16x32_bf16 v[56:59], v[138:141], v[180:183], v[56:59]
	v_mfma_f32_16x16x32_bf16 v[44:47], v[128:131], v[188:191], v[44:47]
	v_mfma_f32_16x16x32_bf16 v[40:43], v[138:141], v[188:191], v[40:43]
	v_mfma_f32_16x16x32_bf16 v[28:31], v[128:131], v[196:199], v[28:31]
	v_mfma_f32_16x16x32_bf16 v[24:27], v[138:141], v[196:199], v[24:27]
	v_mfma_f32_16x16x32_bf16 v[12:15], v[128:131], v[204:207], v[12:15]
	v_mfma_f32_16x16x32_bf16 v[8:11], v[138:141], v[204:207], v[8:11]
	v_mfma_f32_16x16x32_bf16 v[60:63], v[132:135], v[184:187], v[60:63]
	v_mfma_f32_16x16x32_bf16 v[56:59], v[144:147], v[184:187], v[56:59]
	v_mfma_f32_16x16x32_bf16 v[44:47], v[132:135], v[192:195], v[44:47]
	v_mfma_f32_16x16x32_bf16 v[40:43], v[144:147], v[192:195], v[40:43]
	v_mfma_f32_16x16x32_bf16 v[28:31], v[132:135], v[200:203], v[28:31]
	v_mfma_f32_16x16x32_bf16 v[24:27], v[144:147], v[200:203], v[24:27]
	v_mfma_f32_16x16x32_bf16 v[12:15], v[132:135], v[208:211], v[12:15]
	v_mfma_f32_16x16x32_bf16 v[8:11], v[144:147], v[208:211], v[8:11]
	v_mfma_f32_16x16x32_bf16 v[52:55], v[154:157], v[180:183], v[52:55]
	v_mfma_f32_16x16x32_bf16 v[48:51], v[172:175], v[180:183], v[48:51]
	v_mfma_f32_16x16x32_bf16 v[36:39], v[154:157], v[188:191], v[36:39]
	v_mfma_f32_16x16x32_bf16 v[32:35], v[172:175], v[188:191], v[32:35]
	v_mfma_f32_16x16x32_bf16 v[20:23], v[154:157], v[196:199], v[20:23]
	v_mfma_f32_16x16x32_bf16 v[16:19], v[172:175], v[196:199], v[16:19]
	v_mfma_f32_16x16x32_bf16 v[4:7], v[154:157], v[204:207], v[4:7]
	v_mfma_f32_16x16x32_bf16 v[0:3], v[172:175], v[204:207], v[0:3]
	v_mfma_f32_16x16x32_bf16 v[52:55], v[158:161], v[184:187], v[52:55]
	v_mfma_f32_16x16x32_bf16 v[48:51], v[176:179], v[184:187], v[48:51]
	v_mfma_f32_16x16x32_bf16 v[36:39], v[158:161], v[192:195], v[36:39]
	v_mfma_f32_16x16x32_bf16 v[32:35], v[176:179], v[192:195], v[32:35]
	v_mfma_f32_16x16x32_bf16 v[20:23], v[158:161], v[200:203], v[20:23]
	v_mfma_f32_16x16x32_bf16 v[16:19], v[176:179], v[200:203], v[16:19]
	v_mfma_f32_16x16x32_bf16 v[4:7], v[158:161], v[208:211], v[4:7]
	v_mfma_f32_16x16x32_bf16 v[0:3], v[176:179], v[208:211], v[0:3]
	s_setprio 0
	s_barrier
	s_add_i32 s81, s81, 2
	s_add_u32 s4, s4, 0x100
	s_addc_u32 s5, s5, 0
	s_add_u32 s70, s70, 0x100
	s_addc_u32 s72, s72, 0
	s_cmp_gt_u32 s81, 13
	s_cbranch_scc0 .LBB0_591
	s_and_b64 vcc, exec, s[12:13]
	s_cbranch_vccz .LBB0_594
	s_barrier

; #define PG8_LDA(dst, b, h) do { _Pragma("unroll") for (int m = 0; m < 4; ++m) _Pragma("unroll") for (int k = 0; k < 2; ++k) dst[m][k] = *(const LAS bf16x8*)(lds + PG8_SA(b, h) + aoff + m * 2048 + k * 1024); } while (0)
; #define PG8_LDB(dst, b, h) do { _Pragma("unroll") for (int n = 0; n < 2; ++n) _Pragma("unroll") for (int k = 0; k < 2; ++k) dst[n][k] = *(const LAS bf16x8*)(lds + PG8_SB(b, h) + boff + n * 2048 + k * 1024); } while (0)
; #define PG8_MMA(ai, bj, At, Bt) do { __builtin_amdgcn_s_setprio(1); _Pragma("unroll") for (int m = 0; m < 4; ++m) _Pragma("unroll") for (int n = 0; n < 2; ++n) _Pragma("unroll") for (int k = 0; k < 2; ++k) \
;         acc[ai][bj][m][n] = __builtin_amdgcn_mfma_f32_16x16x32_bf16(Bt[n][k], At[m][k], acc[ai][bj][m][n], 0, 0, 0); __builtin_amdgcn_s_setprio(0); } while (0)
; #define PG8_WAIT_V(n) asm volatile("s_waitcnt vmcnt(" #n ")" ::: "memory")
; #define PG8_WAIT_L(n) asm volatile("s_waitcnt lgkmcnt(" #n ")" ::: "memory")
; #define PG8_BAR __builtin_amdgcn_s_barrier()
; #define PG8_SCHED __builtin_amdgcn_sched_barrier(0)
; template <class Epi, bool ALIGN_EPI = true, bool SP2 = true>
; DI void gemm_phase(LAS unsigned char* lds, const Gemm g, const StaticOrder& S, const Epi& E) {
;     ...
;             const bool last = (t == nt - 2);
;             const char* a1 = cA + (size_t)(t + 1) * kstep;
;             const char* a2 = last ? nA : cA + (size_t)(t + 2) * kstep; const char* b2 = last ? nB : cB + (size_t)(t + 2) * kstep;
;             const char* a3 = a2 + kstep; const char* b3 = b2 + kstep;
;             if constexpr (SP2) {
;             PG8_LDB(B0, 0, 0); PG8_LDB(B1, 0, 1); PG8_SCHED; PG8_LDA(At, 0, 0); PG8_STAGE(PG8_SA(1, 1), a1 + hstepA, voffA);
;             PG8_WAIT_V(8); PG8_WAIT_L(0); PG8_BAR; PG8_MMA(0, 0, At, B0); PG8_MMA(0, 1, At, B1); PG8_BAR; PG8_SCHED;
;             PG8_LDA(At, 0, 1); PG8_STAGE(PG8_SB(0, 0), b2, voffB); PG8_STAGE(PG8_SB(0, 1), b2 + hstep, voffB); PG8_STAGE(PG8_SA(0, 0), a2, voffA);
.LBB0_688:
	s_add_i32 s18, s4, 2
	s_cmp_eq_u32 s96, s4
	s_cselect_b32 s46, s0, vcc_lo
	s_cselect_b32 s47, s1, vcc_hi
	s_cselect_b32 s40, s44, s55
	s_cselect_b32 s41, s45, s73
	s_add_u32 s4, s46, 0x80
	s_addc_u32 s5, s47, 0
	s_add_i32 s19, 0, 0x10000
	v_add_u32_e32 v138, s19, v178
	s_add_i32 s8, 0, 0x14000
	ds_read_b128 v[128:131], v138
	ds_read_b128 v[132:135], v138 offset:1024
	ds_read_b128 v[152:155], v138 offset:2048
	ds_read_b128 v[156:159], v138 offset:3072
	v_add_u32_e32 v138, s8, v178
	ds_read_b128 v[180:183], v138
	ds_read_b128 v[184:187], v138 offset:1024
	ds_read_b128 v[188:191], v138 offset:2048
	ds_read_b128 v[192:195], v138 offset:3072
	s_add_u32 s9, vcc_lo, s69
	s_addc_u32 s49, vcc_hi, 0
	s_add_u32 s48, s9, 0xffffff80
	s_addc_u32 s49, s49, -1
	v_mov_b32_e32 v138, v136
	ds_read_b128 v[196:199], v179
	ds_read_b128 v[200:203], v179 offset:1024
	ds_read_b128 v[204:207], v179 offset:2048
	ds_read_b128 v[208:211], v179 offset:3072
	ds_read_b128 v[212:215], v179 offset:4096
	ds_read_b128 v[216:219], v179 offset:5120
	ds_read_b128 v[220:223], v179 offset:6144
	ds_read_b128 v[224:227], v179 offset:7168
	s_add_i32 m0, s86, 0xc000
	s_nop 0
	global_load_lds_dwordx4 v138, s[48:49]
	v_mov_b32_e32 v138, v176
	s_add_i32 m0, s86, 0xe000
	s_nop 0
	global_load_lds_dwordx4 v138, s[48:49]
	s_waitcnt vmcnt(8)
	s_waitcnt lgkmcnt(0)
	s_barrier
	s_setprio 1
	s_waitcnt lgkmcnt(0)
	v_mfma_f32_16x16x32_bf16 v[124:127], v[128:131], v[196:199], v[124:127]
	v_mfma_f32_16x16x32_bf16 v[120:123], v[152:155], v[196:199], v[120:123]
	v_mfma_f32_16x16x32_bf16 v[108:111], v[128:131], v[204:207], v[108:111]
	v_mfma_f32_16x16x32_bf16 v[104:107], v[152:155], v[204:207], v[104:107]
	v_mfma_f32_16x16x32_bf16 v[92:95], v[128:131], v[212:215], v[92:95]
	v_mfma_f32_16x16x32_bf16 v[88:91], v[152:155], v[212:215], v[88:91]
	v_mfma_f32_16x16x32_bf16 v[76:79], v[128:131], v[220:223], v[76:79]
	v_mfma_f32_16x16x32_bf16 v[72:75], v[152:155], v[220:223], v[72:75]
	v_mfma_f32_16x16x32_bf16 v[124:127], v[132:135], v[200:203], v[124:127]
	v_mfma_f32_16x16x32_bf16 v[120:123], v[156:159], v[200:203], v[120:123]
	v_mfma_f32_16x16x32_bf16 v[108:111], v[132:135], v[208:211], v[108:111]
	v_mfma_f32_16x16x32_bf16 v[104:107], v[156:159], v[208:211], v[104:107]
	v_mfma_f32_16x16x32_bf16 v[92:95], v[132:135], v[216:219], v[92:95]
	v_mfma_f32_16x16x32_bf16 v[88:91], v[156:159], v[216:219], v[88:91]
	v_mfma_f32_16x16x32_bf16 v[76:79], v[132:135], v[224:227], v[76:79]
	v_mfma_f32_16x16x32_bf16 v[72:75], v[156:159], v[224:227], v[72:75]
	v_mfma_f32_16x16x32_bf16 v[116:119], v[180:183], v[196:199], v[116:119]
	v_mfma_f32_16x16x32_bf16 v[112:115], v[188:191], v[196:199], v[112:115]
	v_mfma_f32_16x16x32_bf16 v[100:103], v[180:183], v[204:207], v[100:103]
	v_mfma_f32_16x16x32_bf16 v[96:99], v[188:191], v[204:207], v[96:99]
	v_mfma_f32_16x16x32_bf16 v[84:87], v[180:183], v[212:215], v[84:87]
	v_mfma_f32_16x16x32_bf16 v[80:83], v[188:191], v[212:215], v[80:83]
	v_mfma_f32_16x16x32_bf16 v[68:71], v[180:183], v[220:223], v[68:71]
	v_mfma_f32_16x16x32_bf16 v[64:67], v[188:191], v[220:223], v[64:67]
	v_mfma_f32_16x16x32_bf16 v[116:119], v[184:187], v[200:203], v[116:119]
	v_mfma_f32_16x16x32_bf16 v[112:115], v[192:195], v[200:203], v[112:115]
	v_mfma_f32_16x16x32_bf16 v[100:103], v[184:187], v[208:211], v[100:103]
	v_mfma_f32_16x16x32_bf16 v[96:99], v[192:195], v[208:211], v[96:99]
	v_mfma_f32_16x16x32_bf16 v[84:87], v[184:187], v[216:219], v[84:87]
	v_mfma_f32_16x16x32_bf16 v[80:83], v[192:195], v[216:219], v[80:83]
	v_mfma_f32_16x16x32_bf16 v[68:71], v[184:187], v[224:227], v[68:71]
	v_mfma_f32_16x16x32_bf16 v[64:67], v[192:195], v[224:227], v[64:67]
	s_setprio 0
	s_barrier
	s_add_i32 s9, s19, s83
	s_mov_b64 s[48:49], s[40:41]
	v_mov_b32_e32 v138, v143
	s_mov_b32 m0, s9
	ds_read_b128 v[196:199], v179 offset:16384
	ds_read_b128 v[200:203], v179 offset:17408
	ds_read_b128 v[204:207], v179 offset:18432
	ds_read_b128 v[208:211], v179 offset:19456
	ds_read_b128 v[212:215], v179 offset:20480
	ds_read_b128 v[216:219], v179 offset:21504
	ds_read_b128 v[220:223], v179 offset:22528
	ds_read_b128 v[224:227], v179 offset:23552
	s_nop 0
	global_load_lds_dwordx4 v138, s[48:49]
	s_add_i32 m0, s9, 0x2000
	v_mov_b32_e32 v138, v177
	s_add_u32 s94, s40, s54
	s_addc_u32 s95, s41, 0
	global_load_lds_dwordx4 v138, s[48:49]
	s_mov_b64 s[48:49], s[94:95]
	v_mov_b32_e32 v138, v143
	s_add_i32 s8, s8, s83
	s_mov_b32 m0, s8
	s_nop 0
	global_load_lds_dwordx4 v138, s[48:49]
	v_mov_b32_e32 v138, v177
	s_add_i32 m0, s8, 0x2000
	s_nop 0
	global_load_lds_dwordx4 v138, s[48:49]
	s_mov_b64 s[48:49], s[46:47]
	v_mov_b32_e32 v138, v136
	s_mov_b32 m0, s86
	s_nop 0
	global_load_lds_dwordx4 v138, s[48:49]
	v_mov_b32_e32 v138, v176
	s_mov_b32 m0, s92
	s_nop 0
	global_load_lds_dwordx4 v138, s[48:49]
	s_waitcnt vmcnt(8)
	s_waitcnt lgkmcnt(0)
	s_barrier
; #define PG8_LDA(dst, b, h) do { _Pragma("unroll") for (int m = 0; m < 4; ++m) _Pragma("unroll") for (int k = 0; k < 2; ++k) dst[m][k] = *(const LAS bf16x8*)(lds + PG8_SA(b, h) + aoff + m * 2048 + k * 1024); } while (0)
; #define PG8_LDB(dst, b, h) do { _Pragma("unroll") for (int n = 0; n < 2; ++n) _Pragma("unroll") for (int k = 0; k < 2; ++k) dst[n][k] = *(const LAS bf16x8*)(lds + PG8_SB(b, h) + boff + n * 2048 + k * 1024); } while (0)
; #define PG8_MMA(ai, bj, At, Bt) do { __builtin_amdgcn_s_setprio(1); _Pragma("unroll") for (int m = 0; m < 4; ++m) _Pragma("unroll") for (int n = 0; n < 2; ++n) _Pragma("unroll") for (int k = 0; k < 2; ++k) \
;         acc[ai][bj][m][n] = __builtin_amdgcn_mfma_f32_16x16x32_bf16(Bt[n][k], At[m][k], acc[ai][bj][m][n], 0, 0, 0); __builtin_amdgcn_s_setprio(0); } while (0)
; #define PG8_WAIT_V(n) asm volatile("s_waitcnt vmcnt(" #n ")" ::: "memory")
; #define PG8_WAIT_L(n) asm volatile("s_waitcnt lgkmcnt(" #n ")" ::: "memory")
; #define PG8_BAR __builtin_amdgcn_s_barrier()
; #define PG8_SCHED __builtin_amdgcn_sched_barrier(0)
; template <class Epi, bool ALIGN_EPI = true, bool SP2 = true>
; DI void gemm_phase(LAS unsigned char* lds, const Gemm g, const StaticOrder& S, const Epi& E) {
;     ...
;             PG8_WAIT_V(8); PG8_WAIT_L(0); PG8_BAR; PG8_MMA(1, 0, At, B0); PG8_MMA(1, 1, At, B1); PG8_BAR; PG8_SCHED;
;             PG8_LDB(B0, 1, 0); PG8_LDB(B1, 1, 1); PG8_SCHED; PG8_LDA(At, 1, 0); PG8_STAGE(PG8_SA(0, 1), a2 + hstepA, voffA);
;             PG8_WAIT_V(8); PG8_WAIT_L(0); PG8_BAR; PG8_MMA(0, 0, At, B0); PG8_MMA(0, 1, At, B1); PG8_BAR; PG8_SCHED;
	s_setprio 1
	s_waitcnt lgkmcnt(0)
	v_mfma_f32_16x16x32_bf16 v[60:63], v[128:131], v[196:199], v[60:63]
	v_mfma_f32_16x16x32_bf16 v[56:59], v[152:155], v[196:199], v[56:59]
	v_mfma_f32_16x16x32_bf16 v[44:47], v[128:131], v[204:207], v[44:47]
	v_mfma_f32_16x16x32_bf16 v[40:43], v[152:155], v[204:207], v[40:43]
	v_mfma_f32_16x16x32_bf16 v[28:31], v[128:131], v[212:215], v[28:31]
	v_mfma_f32_16x16x32_bf16 v[24:27], v[152:155], v[212:215], v[24:27]
	v_mfma_f32_16x16x32_bf16 v[12:15], v[128:131], v[220:223], v[12:15]
	v_mfma_f32_16x16x32_bf16 v[8:11], v[152:155], v[220:223], v[8:11]
	v_mfma_f32_16x16x32_bf16 v[60:63], v[132:135], v[200:203], v[60:63]
	v_mfma_f32_16x16x32_bf16 v[56:59], v[156:159], v[200:203], v[56:59]
	v_mfma_f32_16x16x32_bf16 v[44:47], v[132:135], v[208:211], v[44:47]
	v_mfma_f32_16x16x32_bf16 v[40:43], v[156:159], v[208:211], v[40:43]
	v_mfma_f32_16x16x32_bf16 v[28:31], v[132:135], v[216:219], v[28:31]
	v_mfma_f32_16x16x32_bf16 v[24:27], v[156:159], v[216:219], v[24:27]
	v_mfma_f32_16x16x32_bf16 v[12:15], v[132:135], v[224:227], v[12:15]
	v_mfma_f32_16x16x32_bf16 v[8:11], v[156:159], v[224:227], v[8:11]
	v_mfma_f32_16x16x32_bf16 v[52:55], v[180:183], v[196:199], v[52:55]
	v_mfma_f32_16x16x32_bf16 v[48:51], v[188:191], v[196:199], v[48:51]
	v_mfma_f32_16x16x32_bf16 v[36:39], v[180:183], v[204:207], v[36:39]
	v_mfma_f32_16x16x32_bf16 v[32:35], v[188:191], v[204:207], v[32:35]
	v_mfma_f32_16x16x32_bf16 v[20:23], v[180:183], v[212:215], v[20:23]
	v_mfma_f32_16x16x32_bf16 v[16:19], v[188:191], v[212:215], v[16:19]
	v_mfma_f32_16x16x32_bf16 v[4:7], v[180:183], v[220:223], v[4:7]
	v_mfma_f32_16x16x32_bf16 v[0:3], v[188:191], v[220:223], v[0:3]
	v_mfma_f32_16x16x32_bf16 v[52:55], v[184:187], v[200:203], v[52:55]
	v_mfma_f32_16x16x32_bf16 v[48:51], v[192:195], v[200:203], v[48:51]
	v_mfma_f32_16x16x32_bf16 v[36:39], v[184:187], v[208:211], v[36:39]
	v_mfma_f32_16x16x32_bf16 v[32:35], v[192:195], v[208:211], v[32:35]
	v_mfma_f32_16x16x32_bf16 v[20:23], v[184:187], v[216:219], v[20:23]
	v_mfma_f32_16x16x32_bf16 v[16:19], v[192:195], v[216:219], v[16:19]
	v_mfma_f32_16x16x32_bf16 v[4:7], v[184:187], v[224:227], v[4:7]
	v_mfma_f32_16x16x32_bf16 v[0:3], v[192:195], v[224:227], v[0:3]
	s_setprio 0
	s_barrier
	s_add_i32 s8, 0, 0x18000
	v_add_u32_e32 v138, s8, v178
	s_add_i32 s9, 0, 0x1c000
	ds_read_b128 v[128:131], v138
	ds_read_b128 v[132:135], v138 offset:1024
	ds_read_b128 v[152:155], v138 offset:2048
	ds_read_b128 v[156:159], v138 offset:3072
	v_add_u32_e32 v138, s9, v178
	ds_read_b128 v[180:183], v138
	ds_read_b128 v[184:187], v138 offset:1024
	ds_read_b128 v[188:191], v138 offset:2048
	ds_read_b128 v[192:195], v138 offset:3072
	s_add_u32 s46, s46, s69
	s_addc_u32 s47, s47, 0
	v_mov_b32_e32 v138, v136
	s_mov_b32 m0, s26
	ds_read_b128 v[196:199], v179 offset:32768
	ds_read_b128 v[200:203], v179 offset:33792
	ds_read_b128 v[204:207], v179 offset:34816
	ds_read_b128 v[208:211], v179 offset:35840
	ds_read_b128 v[212:215], v179 offset:36864
	ds_read_b128 v[216:219], v179 offset:37888
	ds_read_b128 v[220:223], v179 offset:38912
	ds_read_b128 v[224:227], v179 offset:39936
	s_nop 0
	global_load_lds_dwordx4 v138, s[46:47]
	v_mov_b32_e32 v138, v176
	s_mov_b32 m0, s36
	s_nop 0
	global_load_lds_dwordx4 v138, s[46:47]
	s_waitcnt vmcnt(8)
	s_waitcnt lgkmcnt(0)
	s_barrier
	s_setprio 1
	s_waitcnt lgkmcnt(0)
	v_mfma_f32_16x16x32_bf16 v[124:127], v[128:131], v[196:199], v[124:127]
	v_mfma_f32_16x16x32_bf16 v[120:123], v[152:155], v[196:199], v[120:123]
	v_mfma_f32_16x16x32_bf16 v[108:111], v[128:131], v[204:207], v[108:111]
	v_mfma_f32_16x16x32_bf16 v[104:107], v[152:155], v[204:207], v[104:107]
	v_mfma_f32_16x16x32_bf16 v[92:95], v[128:131], v[212:215], v[92:95]
	v_mfma_f32_16x16x32_bf16 v[88:91], v[152:155], v[212:215], v[88:91]
	v_mfma_f32_16x16x32_bf16 v[76:79], v[128:131], v[220:223], v[76:79]
	v_mfma_f32_16x16x32_bf16 v[72:75], v[152:155], v[220:223], v[72:75]
	v_mfma_f32_16x16x32_bf16 v[124:127], v[132:135], v[200:203], v[124:127]
	v_mfma_f32_16x16x32_bf16 v[120:123], v[156:159], v[200:203], v[120:123]
	v_mfma_f32_16x16x32_bf16 v[108:111], v[132:135], v[208:211], v[108:111]
	v_mfma_f32_16x16x32_bf16 v[104:107], v[156:159], v[208:211], v[104:107]
	v_mfma_f32_16x16x32_bf16 v[92:95], v[132:135], v[216:219], v[92:95]
	v_mfma_f32_16x16x32_bf16 v[88:91], v[156:159], v[216:219], v[88:91]
	v_mfma_f32_16x16x32_bf16 v[76:79], v[132:135], v[224:227], v[76:79]
	v_mfma_f32_16x16x32_bf16 v[72:75], v[156:159], v[224:227], v[72:75]
	v_mfma_f32_16x16x32_bf16 v[116:119], v[180:183], v[196:199], v[116:119]
	v_mfma_f32_16x16x32_bf16 v[112:115], v[188:191], v[196:199], v[112:115]
	v_mfma_f32_16x16x32_bf16 v[100:103], v[180:183], v[204:207], v[100:103]
	v_mfma_f32_16x16x32_bf16 v[96:99], v[188:191], v[204:207], v[96:99]
	v_mfma_f32_16x16x32_bf16 v[84:87], v[180:183], v[212:215], v[84:87]
	v_mfma_f32_16x16x32_bf16 v[80:83], v[188:191], v[212:215], v[80:83]
	v_mfma_f32_16x16x32_bf16 v[68:71], v[180:183], v[220:223], v[68:71]
	v_mfma_f32_16x16x32_bf16 v[64:67], v[188:191], v[220:223], v[64:67]
	v_mfma_f32_16x16x32_bf16 v[116:119], v[184:187], v[200:203], v[116:119]
	v_mfma_f32_16x16x32_bf16 v[112:115], v[192:195], v[200:203], v[112:115]
	v_mfma_f32_16x16x32_bf16 v[100:103], v[184:187], v[208:211], v[100:103]
	v_mfma_f32_16x16x32_bf16 v[96:99], v[192:195], v[208:211], v[96:99]
	v_mfma_f32_16x16x32_bf16 v[84:87], v[184:187], v[216:219], v[84:87]
	v_mfma_f32_16x16x32_bf16 v[80:83], v[192:195], v[216:219], v[80:83]
	v_mfma_f32_16x16x32_bf16 v[68:71], v[184:187], v[224:227], v[68:71]
	v_mfma_f32_16x16x32_bf16 v[64:67], v[192:195], v[224:227], v[64:67]
	s_setprio 0
	s_barrier
; #define PG8_LDA(dst, b, h) do { _Pragma("unroll") for (int m = 0; m < 4; ++m) _Pragma("unroll") for (int k = 0; k < 2; ++k) dst[m][k] = *(const LAS bf16x8*)(lds + PG8_SA(b, h) + aoff + m * 2048 + k * 1024); } while (0)
; #define PG8_MMA(ai, bj, At, Bt) do { __builtin_amdgcn_s_setprio(1); _Pragma("unroll") for (int m = 0; m < 4; ++m) _Pragma("unroll") for (int n = 0; n < 2; ++n) _Pragma("unroll") for (int k = 0; k < 2; ++k) \
;         acc[ai][bj][m][n] = __builtin_amdgcn_mfma_f32_16x16x32_bf16(Bt[n][k], At[m][k], acc[ai][bj][m][n], 0, 0, 0); __builtin_amdgcn_s_setprio(0); } while (0)
; #define PG8_WAIT_V(n) asm volatile("s_waitcnt vmcnt(" #n ")" ::: "memory")
; #define PG8_WAIT_L(n) asm volatile("s_waitcnt lgkmcnt(" #n ")" ::: "memory")
; #define PG8_BAR __builtin_amdgcn_s_barrier()
; #define PG8_SCHED __builtin_amdgcn_sched_barrier(0)
; template <class Epi, bool ALIGN_EPI = true, bool SP2 = true>
; DI void gemm_phase(LAS unsigned char* lds, const Gemm g, const StaticOrder& S, const Epi& E) {
;     ...
;             PG8_LDA(At, 1, 1); PG8_STAGE(PG8_SB(1, 0), b3, voffB); PG8_STAGE(PG8_SB(1, 1), b3 + hstep, voffB); PG8_STAGE(PG8_SA(1, 0), a3, voffA);
;             PG8_WAIT_V(8); PG8_WAIT_L(0); PG8_BAR; PG8_MMA(1, 0, At, B0); PG8_MMA(1, 1, At, B1); PG8_BAR; PG8_SCHED;
;     ...
;         if constexpr (ALIGN_EPI) { if (wr == 0) PG8_BAR; }
	s_add_u32 s40, s40, 0x80
	s_addc_u32 s41, s41, 0
	v_mov_b32_e32 v138, v143
	s_add_i32 s8, s8, s83
	ds_read_b128 v[196:199], v179 offset:49152
	ds_read_b128 v[200:203], v179 offset:50176
	ds_read_b128 v[204:207], v179 offset:51200
	ds_read_b128 v[208:211], v179 offset:52224
	ds_read_b128 v[212:215], v179 offset:53248
	ds_read_b128 v[216:219], v179 offset:54272
	ds_read_b128 v[220:223], v179 offset:55296
	ds_read_b128 v[224:227], v179 offset:56320
	s_mov_b32 m0, s8
	s_nop 0
	global_load_lds_dwordx4 v138, s[40:41]
	v_mov_b32_e32 v138, v177
	s_add_i32 m0, s8, 0x2000
	s_nop 0
	global_load_lds_dwordx4 v138, s[40:41]
	s_add_u32 s40, s94, 0x80
	s_addc_u32 s41, s95, 0
	v_mov_b32_e32 v138, v143
	s_add_i32 s8, s9, s83
	s_mov_b32 m0, s8
	s_nop 0
	global_load_lds_dwordx4 v138, s[40:41]
	v_mov_b32_e32 v138, v177
	s_add_i32 m0, s8, 0x2000
	s_nop 0
	global_load_lds_dwordx4 v138, s[40:41]
	v_mov_b32_e32 v138, v136
	s_mov_b32 m0, s12
	s_nop 0
	global_load_lds_dwordx4 v138, s[4:5]
	v_mov_b32_e32 v138, v176
	s_mov_b32 m0, s13
	s_nop 0
	global_load_lds_dwordx4 v138, s[4:5]
	s_waitcnt vmcnt(8)
	s_waitcnt lgkmcnt(0)
	s_barrier
	s_setprio 1
	s_waitcnt lgkmcnt(0)
	v_mfma_f32_16x16x32_bf16 v[60:63], v[128:131], v[196:199], v[60:63]
	v_mfma_f32_16x16x32_bf16 v[56:59], v[152:155], v[196:199], v[56:59]
	v_mfma_f32_16x16x32_bf16 v[44:47], v[128:131], v[204:207], v[44:47]
	v_mfma_f32_16x16x32_bf16 v[40:43], v[152:155], v[204:207], v[40:43]
	v_mfma_f32_16x16x32_bf16 v[28:31], v[128:131], v[212:215], v[28:31]
	v_mfma_f32_16x16x32_bf16 v[24:27], v[152:155], v[212:215], v[24:27]
	v_mfma_f32_16x16x32_bf16 v[12:15], v[128:131], v[220:223], v[12:15]
	v_mfma_f32_16x16x32_bf16 v[8:11], v[152:155], v[220:223], v[8:11]
	v_mfma_f32_16x16x32_bf16 v[60:63], v[132:135], v[200:203], v[60:63]
	v_mfma_f32_16x16x32_bf16 v[56:59], v[156:159], v[200:203], v[56:59]
	v_mfma_f32_16x16x32_bf16 v[44:47], v[132:135], v[208:211], v[44:47]
	v_mfma_f32_16x16x32_bf16 v[40:43], v[156:159], v[208:211], v[40:43]
	v_mfma_f32_16x16x32_bf16 v[28:31], v[132:135], v[216:219], v[28:31]
	v_mfma_f32_16x16x32_bf16 v[24:27], v[156:159], v[216:219], v[24:27]
	v_mfma_f32_16x16x32_bf16 v[12:15], v[132:135], v[224:227], v[12:15]
	v_mfma_f32_16x16x32_bf16 v[8:11], v[156:159], v[224:227], v[8:11]
	v_mfma_f32_16x16x32_bf16 v[52:55], v[180:183], v[196:199], v[52:55]
	v_mfma_f32_16x16x32_bf16 v[48:51], v[188:191], v[196:199], v[48:51]
	v_mfma_f32_16x16x32_bf16 v[36:39], v[180:183], v[204:207], v[36:39]
	v_mfma_f32_16x16x32_bf16 v[32:35], v[188:191], v[204:207], v[32:35]
	v_mfma_f32_16x16x32_bf16 v[20:23], v[180:183], v[212:215], v[20:23]
	v_mfma_f32_16x16x32_bf16 v[16:19], v[188:191], v[212:215], v[16:19]
	v_mfma_f32_16x16x32_bf16 v[4:7], v[180:183], v[220:223], v[4:7]
	v_mfma_f32_16x16x32_bf16 v[0:3], v[188:191], v[220:223], v[0:3]
	v_mfma_f32_16x16x32_bf16 v[52:55], v[184:187], v[200:203], v[52:55]
	v_mfma_f32_16x16x32_bf16 v[48:51], v[192:195], v[200:203], v[48:51]
	v_mfma_f32_16x16x32_bf16 v[36:39], v[184:187], v[208:211], v[36:39]
	v_mfma_f32_16x16x32_bf16 v[32:35], v[192:195], v[208:211], v[32:35]
	v_mfma_f32_16x16x32_bf16 v[20:23], v[184:187], v[216:219], v[20:23]
	v_mfma_f32_16x16x32_bf16 v[16:19], v[192:195], v[216:219], v[16:19]
	v_mfma_f32_16x16x32_bf16 v[4:7], v[184:187], v[224:227], v[4:7]
	v_mfma_f32_16x16x32_bf16 v[0:3], v[192:195], v[224:227], v[0:3]
	s_setprio 0
	s_barrier
	s_add_u32 vcc_lo, vcc_lo, 0x100
	s_addc_u32 vcc_hi, vcc_hi, 0
	s_add_u32 s55, s55, 0x100
	s_addc_u32 s73, s73, 0
	s_cmp_ge_u32 s18, s81
	s_mov_b32 s4, s18
	s_cbranch_scc0 .LBB0_688
	s_and_b64 vcc, exec, s[84:85]
	s_cbranch_vccz .LBB0_691
	s_barrier

; #define PG8_LDA(dst, b, h) do { _Pragma("unroll") for (int m = 0; m < 4; ++m) _Pragma("unroll") for (int k = 0; k < 2; ++k) dst[m][k] = *(const LAS bf16x8*)(lds + PG8_SA(b, h) + aoff + m * 2048 + k * 1024); } while (0)
; #define PG8_LDB(dst, b, h) do { _Pragma("unroll") for (int n = 0; n < 2; ++n) _Pragma("unroll") for (int k = 0; k < 2; ++k) dst[n][k] = *(const LAS bf16x8*)(lds + PG8_SB(b, h) + boff + n * 2048 + k * 1024); } while (0)
; #define PG8_MMA(ai, bj, At, Bt) do { __builtin_amdgcn_s_setprio(1); _Pragma("unroll") for (int m = 0; m < 4; ++m) _Pragma("unroll") for (int n = 0; n < 2; ++n) _Pragma("unroll") for (int k = 0; k < 2; ++k) \
;         acc[ai][bj][m][n] = __builtin_amdgcn_mfma_f32_16x16x32_bf16(Bt[n][k], At[m][k], acc[ai][bj][m][n], 0, 0, 0); __builtin_amdgcn_s_setprio(0); } while (0)
; #define PG8_WAIT_V(n) asm volatile("s_waitcnt vmcnt(" #n ")" ::: "memory")
; #define PG8_WAIT_L(n) asm volatile("s_waitcnt lgkmcnt(" #n ")" ::: "memory")
; #define PG8_BAR __builtin_amdgcn_s_barrier()
; #define PG8_SCHED __builtin_amdgcn_sched_barrier(0)
; template <class Epi, bool ALIGN_EPI = true, bool SP2 = true>
; DI void gemm_phase(LAS unsigned char* lds, const Gemm g, const StaticOrder& S, const Epi& E) {
;     ...
;             const bool last = (t == nt - 2);
;             const char* a1 = cA + (size_t)(t + 1) * kstep;
;             const char* a2 = last ? nA : cA + (size_t)(t + 2) * kstep; const char* b2 = last ? nB : cB + (size_t)(t + 2) * kstep;
;             const char* a3 = a2 + kstep; const char* b3 = b2 + kstep;
;             if constexpr (SP2) {
;             PG8_LDB(B0, 0, 0); PG8_LDB(B1, 0, 1); PG8_SCHED; PG8_LDA(At, 0, 0); PG8_STAGE(PG8_SA(1, 1), a1 + hstepA, voffA);
;             PG8_WAIT_V(8); PG8_WAIT_L(0); PG8_BAR; PG8_MMA(0, 0, At, B0); PG8_MMA(0, 1, At, B1); PG8_BAR; PG8_SCHED;
;             PG8_LDA(At, 0, 1); PG8_STAGE(PG8_SB(0, 0), b2, voffB); PG8_STAGE(PG8_SB(0, 1), b2 + hstep, voffB); PG8_STAGE(PG8_SA(0, 0), a2, voffA);
.LBB0_770:
	s_add_u32 s16, s14, 0xfffc0080
	s_addc_u32 s17, s15, -1
	s_cmp_eq_u32 s81, 12
	s_cselect_b32 s40, s36, s16
	s_cselect_b32 s41, s9, s17
	s_cselect_b32 s18, s38, s70
	s_cselect_b32 s19, s7, s72
	s_add_u32 s16, s40, 0x80
	s_addc_u32 s17, s41, 0
	s_add_i32 s86, 0, 0x10000
	v_add_u32_e32 v128, s86, v134
	s_add_i32 s92, 0, 0x14000
	ds_read_b128 v[148:151], v128
	ds_read_b128 v[152:155], v128 offset:1024
	ds_read_b128 v[156:159], v128 offset:2048
	ds_read_b128 v[176:179], v128 offset:3072
	v_add_u32_e32 v128, s92, v134
	ds_read_b128 v[180:183], v128
	ds_read_b128 v[184:187], v128 offset:1024
	ds_read_b128 v[188:191], v128 offset:2048
	ds_read_b128 v[192:195], v128 offset:3072
	s_mov_b64 s[96:97], s[14:15]
	v_mov_b32_e32 v128, v130
	ds_read_b128 v[196:199], v135
	ds_read_b128 v[200:203], v135 offset:1024
	ds_read_b128 v[204:207], v135 offset:2048
	ds_read_b128 v[208:211], v135 offset:3072
	ds_read_b128 v[212:215], v135 offset:4096
	ds_read_b128 v[216:219], v135 offset:5120
	ds_read_b128 v[220:223], v135 offset:6144
	ds_read_b128 v[224:227], v135 offset:7168
	s_add_i32 m0, s47, 0xc000
	s_nop 0
	global_load_lds_dwordx4 v128, s[96:97]
	v_mov_b32_e32 v128, v132
	s_add_i32 m0, s47, 0xe000
	s_nop 0
	global_load_lds_dwordx4 v128, s[96:97]
	s_waitcnt vmcnt(8)
	s_waitcnt lgkmcnt(0)
	s_barrier
	s_setprio 1
	s_waitcnt lgkmcnt(0)
	v_mfma_f32_16x16x32_bf16 v[124:127], v[148:151], v[196:199], v[124:127]
	v_mfma_f32_16x16x32_bf16 v[116:119], v[156:159], v[196:199], v[116:119]
	v_mfma_f32_16x16x32_bf16 v[108:111], v[148:151], v[204:207], v[108:111]
	v_mfma_f32_16x16x32_bf16 v[100:103], v[156:159], v[204:207], v[100:103]
	v_mfma_f32_16x16x32_bf16 v[92:95], v[148:151], v[212:215], v[92:95]
	v_mfma_f32_16x16x32_bf16 v[84:87], v[156:159], v[212:215], v[84:87]
	v_mfma_f32_16x16x32_bf16 v[76:79], v[148:151], v[220:223], v[76:79]
	v_mfma_f32_16x16x32_bf16 v[68:71], v[156:159], v[220:223], v[68:71]
	v_mfma_f32_16x16x32_bf16 v[124:127], v[152:155], v[200:203], v[124:127]
	v_mfma_f32_16x16x32_bf16 v[116:119], v[176:179], v[200:203], v[116:119]
	v_mfma_f32_16x16x32_bf16 v[108:111], v[152:155], v[208:211], v[108:111]
	v_mfma_f32_16x16x32_bf16 v[100:103], v[176:179], v[208:211], v[100:103]
	v_mfma_f32_16x16x32_bf16 v[92:95], v[152:155], v[216:219], v[92:95]
	v_mfma_f32_16x16x32_bf16 v[84:87], v[176:179], v[216:219], v[84:87]
	v_mfma_f32_16x16x32_bf16 v[76:79], v[152:155], v[224:227], v[76:79]
	v_mfma_f32_16x16x32_bf16 v[68:71], v[176:179], v[224:227], v[68:71]
	v_mfma_f32_16x16x32_bf16 v[120:123], v[180:183], v[196:199], v[120:123]
	v_mfma_f32_16x16x32_bf16 v[112:115], v[188:191], v[196:199], v[112:115]
	v_mfma_f32_16x16x32_bf16 v[104:107], v[180:183], v[204:207], v[104:107]
	v_mfma_f32_16x16x32_bf16 v[96:99], v[188:191], v[204:207], v[96:99]
	v_mfma_f32_16x16x32_bf16 v[88:91], v[180:183], v[212:215], v[88:91]
	v_mfma_f32_16x16x32_bf16 v[80:83], v[188:191], v[212:215], v[80:83]
	v_mfma_f32_16x16x32_bf16 v[72:75], v[180:183], v[220:223], v[72:75]
	v_mfma_f32_16x16x32_bf16 v[64:67], v[188:191], v[220:223], v[64:67]
	v_mfma_f32_16x16x32_bf16 v[120:123], v[184:187], v[200:203], v[120:123]
	v_mfma_f32_16x16x32_bf16 v[112:115], v[192:195], v[200:203], v[112:115]
	v_mfma_f32_16x16x32_bf16 v[104:107], v[184:187], v[208:211], v[104:107]
	v_mfma_f32_16x16x32_bf16 v[96:99], v[192:195], v[208:211], v[96:99]
	v_mfma_f32_16x16x32_bf16 v[88:91], v[184:187], v[216:219], v[88:91]
	v_mfma_f32_16x16x32_bf16 v[80:83], v[192:195], v[216:219], v[80:83]
	v_mfma_f32_16x16x32_bf16 v[72:75], v[184:187], v[224:227], v[72:75]
	v_mfma_f32_16x16x32_bf16 v[64:67], v[192:195], v[224:227], v[64:67]
	s_setprio 0
	s_barrier
	s_mov_b64 s[96:97], s[18:19]
	v_mov_b32_e32 v128, v131
	s_add_i32 s86, s86, s46
	ds_read_b128 v[196:199], v135 offset:16384
	ds_read_b128 v[200:203], v135 offset:17408
	ds_read_b128 v[204:207], v135 offset:18432
	ds_read_b128 v[208:211], v135 offset:19456
	ds_read_b128 v[212:215], v135 offset:20480
	ds_read_b128 v[216:219], v135 offset:21504
	ds_read_b128 v[220:223], v135 offset:22528
	ds_read_b128 v[224:227], v135 offset:23552
	s_mov_b32 m0, s86
	s_nop 0
	global_load_lds_dwordx4 v128, s[96:97]
	v_mov_b32_e32 v128, v133
	s_add_i32 m0, s86, 0x2000
	s_nop 0
	global_load_lds_dwordx4 v128, s[96:97]
	s_add_u32 s96, s18, 0x40000
	s_addc_u32 s97, s19, 0
	v_mov_b32_e32 v128, v131
	s_add_i32 s86, s92, s46
	s_mov_b32 m0, s86
	s_nop 0
	global_load_lds_dwordx4 v128, s[96:97]
	v_mov_b32_e32 v128, v133
	s_add_i32 m0, s86, 0x2000
	s_nop 0
	global_load_lds_dwordx4 v128, s[96:97]
	s_mov_b64 s[96:97], s[40:41]
	v_mov_b32_e32 v128, v130
	s_mov_b32 m0, s47
	s_nop 0
	global_load_lds_dwordx4 v128, s[96:97]
	v_mov_b32_e32 v128, v132
	s_mov_b32 m0, s48
	s_nop 0
	global_load_lds_dwordx4 v128, s[96:97]
	s_waitcnt vmcnt(8)
	s_waitcnt lgkmcnt(0)
	s_barrier
; #define PG8_LDA(dst, b, h) do { _Pragma("unroll") for (int m = 0; m < 4; ++m) _Pragma("unroll") for (int k = 0; k < 2; ++k) dst[m][k] = *(const LAS bf16x8*)(lds + PG8_SA(b, h) + aoff + m * 2048 + k * 1024); } while (0)
; #define PG8_LDB(dst, b, h) do { _Pragma("unroll") for (int n = 0; n < 2; ++n) _Pragma("unroll") for (int k = 0; k < 2; ++k) dst[n][k] = *(const LAS bf16x8*)(lds + PG8_SB(b, h) + boff + n * 2048 + k * 1024); } while (0)
; #define PG8_MMA(ai, bj, At, Bt) do { __builtin_amdgcn_s_setprio(1); _Pragma("unroll") for (int m = 0; m < 4; ++m) _Pragma("unroll") for (int n = 0; n < 2; ++n) _Pragma("unroll") for (int k = 0; k < 2; ++k) \
;         acc[ai][bj][m][n] = __builtin_amdgcn_mfma_f32_16x16x32_bf16(Bt[n][k], At[m][k], acc[ai][bj][m][n], 0, 0, 0); __builtin_amdgcn_s_setprio(0); } while (0)
; #define PG8_WAIT_V(n) asm volatile("s_waitcnt vmcnt(" #n ")" ::: "memory")
; #define PG8_WAIT_L(n) asm volatile("s_waitcnt lgkmcnt(" #n ")" ::: "memory")
; #define PG8_BAR __builtin_amdgcn_s_barrier()
; #define PG8_SCHED __builtin_amdgcn_sched_barrier(0)
; template <class Epi, bool ALIGN_EPI = true, bool SP2 = true>
; DI void gemm_phase(LAS unsigned char* lds, const Gemm g, const StaticOrder& S, const Epi& E) {
;     ...
;             PG8_WAIT_V(8); PG8_WAIT_L(0); PG8_BAR; PG8_MMA(1, 0, At, B0); PG8_MMA(1, 1, At, B1); PG8_BAR; PG8_SCHED;
;             PG8_LDB(B0, 1, 0); PG8_LDB(B1, 1, 1); PG8_SCHED; PG8_LDA(At, 1, 0); PG8_STAGE(PG8_SA(0, 1), a2 + hstepA, voffA);
;             PG8_WAIT_V(8); PG8_WAIT_L(0); PG8_BAR; PG8_MMA(0, 0, At, B0); PG8_MMA(0, 1, At, B1); PG8_BAR; PG8_SCHED;
	s_setprio 1
	s_waitcnt lgkmcnt(0)
	v_mfma_f32_16x16x32_bf16 v[60:63], v[148:151], v[196:199], v[60:63]
	v_mfma_f32_16x16x32_bf16 v[52:55], v[156:159], v[196:199], v[52:55]
	v_mfma_f32_16x16x32_bf16 v[44:47], v[148:151], v[204:207], v[44:47]
	v_mfma_f32_16x16x32_bf16 v[36:39], v[156:159], v[204:207], v[36:39]
	v_mfma_f32_16x16x32_bf16 v[28:31], v[148:151], v[212:215], v[28:31]
	v_mfma_f32_16x16x32_bf16 v[20:23], v[156:159], v[212:215], v[20:23]
	v_mfma_f32_16x16x32_bf16 v[12:15], v[148:151], v[220:223], v[12:15]
	v_mfma_f32_16x16x32_bf16 v[4:7], v[156:159], v[220:223], v[4:7]
	v_mfma_f32_16x16x32_bf16 v[60:63], v[152:155], v[200:203], v[60:63]
	v_mfma_f32_16x16x32_bf16 v[52:55], v[176:179], v[200:203], v[52:55]
	v_mfma_f32_16x16x32_bf16 v[44:47], v[152:155], v[208:211], v[44:47]
	v_mfma_f32_16x16x32_bf16 v[36:39], v[176:179], v[208:211], v[36:39]
	v_mfma_f32_16x16x32_bf16 v[28:31], v[152:155], v[216:219], v[28:31]
	v_mfma_f32_16x16x32_bf16 v[20:23], v[176:179], v[216:219], v[20:23]
	v_mfma_f32_16x16x32_bf16 v[12:15], v[152:155], v[224:227], v[12:15]
	v_mfma_f32_16x16x32_bf16 v[4:7], v[176:179], v[224:227], v[4:7]
	v_mfma_f32_16x16x32_bf16 v[56:59], v[180:183], v[196:199], v[56:59]
	v_mfma_f32_16x16x32_bf16 v[48:51], v[188:191], v[196:199], v[48:51]
	v_mfma_f32_16x16x32_bf16 v[40:43], v[180:183], v[204:207], v[40:43]
	v_mfma_f32_16x16x32_bf16 v[32:35], v[188:191], v[204:207], v[32:35]
	v_mfma_f32_16x16x32_bf16 v[24:27], v[180:183], v[212:215], v[24:27]
	v_mfma_f32_16x16x32_bf16 v[16:19], v[188:191], v[212:215], v[16:19]
	v_mfma_f32_16x16x32_bf16 v[8:11], v[180:183], v[220:223], v[8:11]
	v_mfma_f32_16x16x32_bf16 v[0:3], v[188:191], v[220:223], v[0:3]
	v_mfma_f32_16x16x32_bf16 v[56:59], v[184:187], v[200:203], v[56:59]
	v_mfma_f32_16x16x32_bf16 v[48:51], v[192:195], v[200:203], v[48:51]
	v_mfma_f32_16x16x32_bf16 v[40:43], v[184:187], v[208:211], v[40:43]
	v_mfma_f32_16x16x32_bf16 v[32:35], v[192:195], v[208:211], v[32:35]
	v_mfma_f32_16x16x32_bf16 v[24:27], v[184:187], v[216:219], v[24:27]
	v_mfma_f32_16x16x32_bf16 v[16:19], v[192:195], v[216:219], v[16:19]
	v_mfma_f32_16x16x32_bf16 v[8:11], v[184:187], v[224:227], v[8:11]
	v_mfma_f32_16x16x32_bf16 v[0:3], v[192:195], v[224:227], v[0:3]
	s_setprio 0
	s_barrier
	s_add_i32 s86, 0, 0x18000
	v_add_u32_e32 v128, s86, v134
	s_add_i32 s92, 0, 0x1c000
	ds_read_b128 v[148:151], v128
	ds_read_b128 v[152:155], v128 offset:1024
	ds_read_b128 v[156:159], v128 offset:2048
	ds_read_b128 v[176:179], v128 offset:3072
	v_add_u32_e32 v128, s92, v134
	ds_read_b128 v[180:183], v128
	ds_read_b128 v[184:187], v128 offset:1024
	ds_read_b128 v[188:191], v128 offset:2048
	ds_read_b128 v[192:195], v128 offset:3072
	s_add_u32 s40, s40, 0x40000
	s_addc_u32 s41, s41, 0
	v_mov_b32_e32 v128, v130
	s_mov_b32 m0, s49
	ds_read_b128 v[196:199], v135 offset:32768
	ds_read_b128 v[200:203], v135 offset:33792
	ds_read_b128 v[204:207], v135 offset:34816
	ds_read_b128 v[208:211], v135 offset:35840
	ds_read_b128 v[212:215], v135 offset:36864
	ds_read_b128 v[216:219], v135 offset:37888
	ds_read_b128 v[220:223], v135 offset:38912
	ds_read_b128 v[224:227], v135 offset:39936
	s_nop 0
	global_load_lds_dwordx4 v128, s[40:41]
	v_mov_b32_e32 v128, v132
	s_mov_b32 m0, s54
	s_nop 0
	global_load_lds_dwordx4 v128, s[40:41]
	s_waitcnt vmcnt(8)
	s_waitcnt lgkmcnt(0)
	s_barrier
	s_setprio 1
	s_waitcnt lgkmcnt(0)
	v_mfma_f32_16x16x32_bf16 v[124:127], v[148:151], v[196:199], v[124:127]
	v_mfma_f32_16x16x32_bf16 v[116:119], v[156:159], v[196:199], v[116:119]
	v_mfma_f32_16x16x32_bf16 v[108:111], v[148:151], v[204:207], v[108:111]
	v_mfma_f32_16x16x32_bf16 v[100:103], v[156:159], v[204:207], v[100:103]
	v_mfma_f32_16x16x32_bf16 v[92:95], v[148:151], v[212:215], v[92:95]
	v_mfma_f32_16x16x32_bf16 v[84:87], v[156:159], v[212:215], v[84:87]
	v_mfma_f32_16x16x32_bf16 v[76:79], v[148:151], v[220:223], v[76:79]
	v_mfma_f32_16x16x32_bf16 v[68:71], v[156:159], v[220:223], v[68:71]
	v_mfma_f32_16x16x32_bf16 v[124:127], v[152:155], v[200:203], v[124:127]
	v_mfma_f32_16x16x32_bf16 v[116:119], v[176:179], v[200:203], v[116:119]
	v_mfma_f32_16x16x32_bf16 v[108:111], v[152:155], v[208:211], v[108:111]
	v_mfma_f32_16x16x32_bf16 v[100:103], v[176:179], v[208:211], v[100:103]
	v_mfma_f32_16x16x32_bf16 v[92:95], v[152:155], v[216:219], v[92:95]
	v_mfma_f32_16x16x32_bf16 v[84:87], v[176:179], v[216:219], v[84:87]
	v_mfma_f32_16x16x32_bf16 v[76:79], v[152:155], v[224:227], v[76:79]
	v_mfma_f32_16x16x32_bf16 v[68:71], v[176:179], v[224:227], v[68:71]
	v_mfma_f32_16x16x32_bf16 v[120:123], v[180:183], v[196:199], v[120:123]
	v_mfma_f32_16x16x32_bf16 v[112:115], v[188:191], v[196:199], v[112:115]
	v_mfma_f32_16x16x32_bf16 v[104:107], v[180:183], v[204:207], v[104:107]
	v_mfma_f32_16x16x32_bf16 v[96:99], v[188:191], v[204:207], v[96:99]
	v_mfma_f32_16x16x32_bf16 v[88:91], v[180:183], v[212:215], v[88:91]
	v_mfma_f32_16x16x32_bf16 v[80:83], v[188:191], v[212:215], v[80:83]
	v_mfma_f32_16x16x32_bf16 v[72:75], v[180:183], v[220:223], v[72:75]
	v_mfma_f32_16x16x32_bf16 v[64:67], v[188:191], v[220:223], v[64:67]
	v_mfma_f32_16x16x32_bf16 v[120:123], v[184:187], v[200:203], v[120:123]
	v_mfma_f32_16x16x32_bf16 v[112:115], v[192:195], v[200:203], v[112:115]
	v_mfma_f32_16x16x32_bf16 v[104:107], v[184:187], v[208:211], v[104:107]
	v_mfma_f32_16x16x32_bf16 v[96:99], v[192:195], v[208:211], v[96:99]
	v_mfma_f32_16x16x32_bf16 v[88:91], v[184:187], v[216:219], v[88:91]
	v_mfma_f32_16x16x32_bf16 v[80:83], v[192:195], v[216:219], v[80:83]
	v_mfma_f32_16x16x32_bf16 v[72:75], v[184:187], v[224:227], v[72:75]
	v_mfma_f32_16x16x32_bf16 v[64:67], v[192:195], v[224:227], v[64:67]
	s_setprio 0
	s_barrier
; #define PG8_LDA(dst, b, h) do { _Pragma("unroll") for (int m = 0; m < 4; ++m) _Pragma("unroll") for (int k = 0; k < 2; ++k) dst[m][k] = *(const LAS bf16x8*)(lds + PG8_SA(b, h) + aoff + m * 2048 + k * 1024); } while (0)
; #define PG8_MMA(ai, bj, At, Bt) do { __builtin_amdgcn_s_setprio(1); _Pragma("unroll") for (int m = 0; m < 4; ++m) _Pragma("unroll") for (int n = 0; n < 2; ++n) _Pragma("unroll") for (int k = 0; k < 2; ++k) \
;         acc[ai][bj][m][n] = __builtin_amdgcn_mfma_f32_16x16x32_bf16(Bt[n][k], At[m][k], acc[ai][bj][m][n], 0, 0, 0); __builtin_amdgcn_s_setprio(0); } while (0)
; #define PG8_WAIT_V(n) asm volatile("s_waitcnt vmcnt(" #n ")" ::: "memory")
; #define PG8_WAIT_L(n) asm volatile("s_waitcnt lgkmcnt(" #n ")" ::: "memory")
; #define PG8_BAR __builtin_amdgcn_s_barrier()
; #define PG8_SCHED __builtin_amdgcn_sched_barrier(0)
; template <class Epi, bool ALIGN_EPI = true, bool SP2 = true>
; DI void gemm_phase(LAS unsigned char* lds, const Gemm g, const StaticOrder& S, const Epi& E) {
;     ...
;             PG8_LDA(At, 1, 1); PG8_STAGE(PG8_SB(1, 0), b3, voffB); PG8_STAGE(PG8_SB(1, 1), b3 + hstep, voffB); PG8_STAGE(PG8_SA(1, 0), a3, voffA);
;             PG8_WAIT_V(8); PG8_WAIT_L(0); PG8_BAR; PG8_MMA(1, 0, At, B0); PG8_MMA(1, 1, At, B1); PG8_BAR; PG8_SCHED;
;     ...
;         if constexpr (ALIGN_EPI) { if (wr == 0) PG8_BAR; }
	s_add_u32 s40, s18, 0x80
	s_addc_u32 s41, s19, 0
	v_mov_b32_e32 v128, v131
	s_add_i32 s86, s86, s46
	ds_read_b128 v[196:199], v135 offset:49152
	ds_read_b128 v[200:203], v135 offset:50176
	ds_read_b128 v[204:207], v135 offset:51200
	ds_read_b128 v[208:211], v135 offset:52224
	ds_read_b128 v[212:215], v135 offset:53248
	ds_read_b128 v[216:219], v135 offset:54272
	ds_read_b128 v[220:223], v135 offset:55296
	ds_read_b128 v[224:227], v135 offset:56320
	s_mov_b32 m0, s86
	s_nop 0
	global_load_lds_dwordx4 v128, s[40:41]
	v_mov_b32_e32 v128, v133
	s_add_i32 m0, s86, 0x2000
	s_add_u32 s18, s18, 0x40080
	global_load_lds_dwordx4 v128, s[40:41]
	s_addc_u32 s19, s19, 0
	v_mov_b32_e32 v128, v131
	s_add_i32 s40, s92, s46
	s_mov_b32 m0, s40
	s_nop 0
	global_load_lds_dwordx4 v128, s[18:19]
	v_mov_b32_e32 v128, v133
	s_add_i32 m0, s40, 0x2000
	s_nop 0
	global_load_lds_dwordx4 v128, s[18:19]
	v_mov_b32_e32 v128, v130
	s_mov_b32 m0, s69
	s_nop 0
	global_load_lds_dwordx4 v128, s[16:17]
	v_mov_b32_e32 v128, v132
	s_mov_b32 m0, s73
	s_nop 0
	global_load_lds_dwordx4 v128, s[16:17]
	s_waitcnt vmcnt(8)
	s_waitcnt lgkmcnt(0)
	s_barrier
	s_setprio 1
	s_waitcnt lgkmcnt(0)
	v_mfma_f32_16x16x32_bf16 v[60:63], v[148:151], v[196:199], v[60:63]
	v_mfma_f32_16x16x32_bf16 v[52:55], v[156:159], v[196:199], v[52:55]
	v_mfma_f32_16x16x32_bf16 v[44:47], v[148:151], v[204:207], v[44:47]
	v_mfma_f32_16x16x32_bf16 v[36:39], v[156:159], v[204:207], v[36:39]
	v_mfma_f32_16x16x32_bf16 v[28:31], v[148:151], v[212:215], v[28:31]
	v_mfma_f32_16x16x32_bf16 v[20:23], v[156:159], v[212:215], v[20:23]
	v_mfma_f32_16x16x32_bf16 v[12:15], v[148:151], v[220:223], v[12:15]
	v_mfma_f32_16x16x32_bf16 v[4:7], v[156:159], v[220:223], v[4:7]
	v_mfma_f32_16x16x32_bf16 v[60:63], v[152:155], v[200:203], v[60:63]
	v_mfma_f32_16x16x32_bf16 v[52:55], v[176:179], v[200:203], v[52:55]
	v_mfma_f32_16x16x32_bf16 v[44:47], v[152:155], v[208:211], v[44:47]
	v_mfma_f32_16x16x32_bf16 v[36:39], v[176:179], v[208:211], v[36:39]
	v_mfma_f32_16x16x32_bf16 v[28:31], v[152:155], v[216:219], v[28:31]
	v_mfma_f32_16x16x32_bf16 v[20:23], v[176:179], v[216:219], v[20:23]
	v_mfma_f32_16x16x32_bf16 v[12:15], v[152:155], v[224:227], v[12:15]
	v_mfma_f32_16x16x32_bf16 v[4:7], v[176:179], v[224:227], v[4:7]
	v_mfma_f32_16x16x32_bf16 v[56:59], v[180:183], v[196:199], v[56:59]
	v_mfma_f32_16x16x32_bf16 v[48:51], v[188:191], v[196:199], v[48:51]
	v_mfma_f32_16x16x32_bf16 v[40:43], v[180:183], v[204:207], v[40:43]
	v_mfma_f32_16x16x32_bf16 v[32:35], v[188:191], v[204:207], v[32:35]
	v_mfma_f32_16x16x32_bf16 v[24:27], v[180:183], v[212:215], v[24:27]
	v_mfma_f32_16x16x32_bf16 v[16:19], v[188:191], v[212:215], v[16:19]
	v_mfma_f32_16x16x32_bf16 v[8:11], v[180:183], v[220:223], v[8:11]
	v_mfma_f32_16x16x32_bf16 v[0:3], v[188:191], v[220:223], v[0:3]
	v_mfma_f32_16x16x32_bf16 v[56:59], v[184:187], v[200:203], v[56:59]
	v_mfma_f32_16x16x32_bf16 v[48:51], v[192:195], v[200:203], v[48:51]
	v_mfma_f32_16x16x32_bf16 v[40:43], v[184:187], v[208:211], v[40:43]
	v_mfma_f32_16x16x32_bf16 v[32:35], v[192:195], v[208:211], v[32:35]
	v_mfma_f32_16x16x32_bf16 v[24:27], v[184:187], v[216:219], v[24:27]
	v_mfma_f32_16x16x32_bf16 v[16:19], v[192:195], v[216:219], v[16:19]
	v_mfma_f32_16x16x32_bf16 v[8:11], v[184:187], v[224:227], v[8:11]
	v_mfma_f32_16x16x32_bf16 v[0:3], v[192:195], v[224:227], v[0:3]
	s_setprio 0
	s_barrier
	s_add_i32 s81, s81, 2
	s_add_u32 s14, s14, 0x100
	s_addc_u32 s15, s15, 0
	s_add_u32 s70, s70, 0x100
	s_addc_u32 s72, s72, 0
	s_cmp_gt_u32 s81, 13
	s_cbranch_scc0 .LBB0_770
	s_and_b64 vcc, exec, s[4:5]
	s_cbranch_vccz .LBB0_773
	s_barrier
